# non-BAR fragment read runs: V fragments issued before the two hoisted K fragments (P.V ladder +2)
# speedup vs baseline: 1.0066x; 1.0010x over previous
.LBB0_641:
	s_add_i32 s24, s23, -7
	s_lshl_b32 s92, s24, 13
	s_add_u32 vcc_lo, s100, s92
	s_addc_u32 vcc_hi, s101, 0
	global_load_dwordx4 v[52:55], v248, vcc
	s_add_i32 s24, s23, -8
	s_lshl_b32 s92, s24, 7
	s_add_u32 vcc_lo, s98, s92
	s_addc_u32 vcc_hi, s99, 0
	global_load_dwordx4 v[56:59], v249, vcc
	s_mul_i32 s26, s25, 0x2400
	s_add_i32 s24, s23, -7
	s_add_i32 s27, s26, 0xffffdc00
	s_cmp_lg_u32 s25, 0
	s_cselect_b32 s27, s27, 0x9000
	v_add_u32_e32 v1, s27, v163
	ds_read_b128 v[60:63], v1 offset:36864
	ds_read_b128 v[114:117], v1 offset:36896
	ds_read_b128 v[118:121], v1 offset:41472
	ds_read_b128 v[134:137], v1 offset:41504
	ds_read_b128 v[146:149], v1 offset:36928
	ds_read_b128 v[150:153], v1 offset:36960
	ds_read_b128 v[196:199], v1 offset:41536
	ds_read_b128 v[200:203], v1 offset:41568
	s_setprio 3
	v_cvt_pk_bf16_f32 v204, v102, v103
	v_cvt_pk_bf16_f32 v205, v104, v105
	v_cvt_pk_bf16_f32 v206, v98, v99
	v_cvt_pk_bf16_f32 v207, v100, v101
	s_waitcnt lgkmcnt(7)
	s_nop 0
	v_mfma_f32_32x32x16_bf16 v[18:33], v[60:63], v[204:207], v[18:33]
	v_add_f32_e32 v1, v102, v103
	v_add_f32_e32 v1, v1, v104
	v_add_f32_e32 v1, v1, v105
	s_waitcnt lgkmcnt(5)
	v_mfma_f32_32x32x16_bf16 v[2:17], v[118:121], v[204:207], v[2:17]
	v_cvt_pk_bf16_f32 v60, v194, v187
	v_cvt_pk_bf16_f32 v61, v186, v185
	v_cvt_pk_bf16_f32 v62, v133, v132
	v_cvt_pk_bf16_f32 v63, v131, v130
	v_add_f32_e32 v1, v1, v98
	v_add_f32_e32 v1, v1, v99
	v_add_f32_e32 v1, v1, v100
	v_add_f32_e32 v1, v1, v101
	s_nop 0
	v_mfma_f32_32x32x16_bf16 v[18:33], v[114:117], v[60:63], v[18:33]
	v_add_f32_e32 v1, v1, v194
	v_add_f32_e32 v1, v1, v187
	v_add_f32_e32 v1, v1, v186
	v_add_f32_e32 v1, v1, v185
	s_waitcnt lgkmcnt(4)
	v_mfma_f32_32x32x16_bf16 v[2:17], v[134:137], v[60:63], v[2:17]
	v_cvt_pk_bf16_f32 v98, v129, v128
	v_cvt_pk_bf16_f32 v99, v127, v126
	v_cvt_pk_bf16_f32 v100, v125, v124
	v_cvt_pk_bf16_f32 v101, v123, v122
	v_add_f32_e32 v1, v1, v133
	v_add_f32_e32 v1, v1, v132
	v_add_f32_e32 v1, v1, v131
	v_add_f32_e32 v1, v1, v130
	s_waitcnt lgkmcnt(3)
	v_mfma_f32_32x32x16_bf16 v[18:33], v[146:149], v[98:101], v[18:33]
	v_add_f32_e32 v1, v1, v129
	v_add_f32_e32 v1, v1, v128
	v_add_f32_e32 v1, v1, v127
	v_add_f32_e32 v1, v1, v126
	s_waitcnt lgkmcnt(1)
	v_mfma_f32_32x32x16_bf16 v[2:17], v[196:199], v[98:101], v[2:17]
	v_cvt_pk_bf16_f32 v60, v109, v108
	v_cvt_pk_bf16_f32 v61, v107, v106
	v_cvt_pk_bf16_f32 v62, v113, v112
	v_cvt_pk_bf16_f32 v63, v111, v110
	v_add_f32_e32 v1, v1, v125
	v_add_f32_e32 v1, v1, v124
	v_add_f32_e32 v1, v1, v123
	v_add_f32_e32 v1, v1, v122
	s_nop 0
	v_mfma_f32_32x32x16_bf16 v[18:33], v[150:153], v[60:63], v[18:33]
	v_add_f32_e32 v1, v1, v109
	v_add_f32_e32 v1, v1, v108
	v_add_f32_e32 v1, v1, v107
	v_add_f32_e32 v1, v1, v106
	s_waitcnt lgkmcnt(0)
	v_mfma_f32_32x32x16_bf16 v[2:17], v[200:203], v[60:63], v[2:17]
	v_add_f32_e32 v1, v1, v113
	v_add_f32_e32 v1, v1, v112
	v_add_f32_e32 v1, v1, v111
	v_add_f32_e32 v1, v1, v110
	s_setprio 2
	s_waitcnt lgkmcnt(0)
	s_barrier
	ds_read_b128 v[240:243], v165 offset:18432
	ds_read_b128 v[244:247], v165 offset:23040
	ds_read_b128 v[130:133], v165 offset:18464
	ds_read_b128 v[146:149], v165 offset:23072
	v_exp_f32_e32 v185, v82
	v_exp_f32_e32 v186, v83
	v_exp_f32_e32 v187, v84
	v_exp_f32_e32 v194, v85
	v_exp_f32_e32 v195, v86
	v_exp_f32_e32 v196, v87
	v_exp_f32_e32 v197, v88
	v_exp_f32_e32 v198, v89
	s_waitcnt lgkmcnt(2)
	v_mfma_f32_32x32x16_bf16 v[114:129], v[240:243], v[158:161], v[34:49]
	s_waitcnt lgkmcnt(1)
	v_mfma_f32_32x32x16_bf16 v[98:113], v[244:247], v[158:161], v[34:49]
	v_exp_f32_e32 v199, v90
	v_exp_f32_e32 v200, v91
	v_exp_f32_e32 v201, v92
	v_exp_f32_e32 v202, v93
	v_exp_f32_e32 v134, v94
	v_exp_f32_e32 v135, v95
	v_exp_f32_e32 v136, v96
	v_exp_f32_e32 v137, v97
	v_mfma_f32_32x32x16_bf16 v[114:129], v[130:133], v[154:157], v[114:129]
	v_exp_f32_e32 v96, v66
	v_exp_f32_e32 v97, v67
	v_exp_f32_e32 v203, v68
	v_exp_f32_e32 v204, v69
	v_exp_f32_e32 v130, v70
	v_exp_f32_e32 v131, v71
	v_exp_f32_e32 v132, v72
	v_exp_f32_e32 v133, v73
	s_waitcnt lgkmcnt(0)
	v_mfma_f32_32x32x16_bf16 v[98:113], v[146:149], v[154:157], v[98:113]
	v_exp_f32_e32 v205, v74
	v_exp_f32_e32 v206, v75
	v_exp_f32_e32 v207, v76
	v_exp_f32_e32 v208, v77
	v_exp_f32_e32 v209, v78
	v_exp_f32_e32 v210, v79
	v_exp_f32_e32 v211, v80
	v_exp_f32_e32 v212, v81
	v_add_u32_e32 v88, s26, v163
	ds_read_b128 v[60:63], v88 offset:41472
	ds_read_b128 v[64:67], v88 offset:36864
	ds_read_b128 v[68:71], v88 offset:36896
	ds_read_b128 v[72:75], v88 offset:41504
	ds_read_b128 v[76:79], v88 offset:36928
	ds_read_b128 v[80:83], v88 offset:41536
	ds_read_b128 v[84:87], v88 offset:36960
	ds_read_b128 v[88:91], v88 offset:41568
	ds_read_b128 v[240:243], v165 offset:27648
	ds_read_b128 v[244:247], v165 offset:32256
	s_cmp_gt_i32 s25, 2
	s_cselect_b32 s27, -3, 2
	s_add_i32 s27, s27, s25
	s_add_i32 s26, s23, -6
	s_mulk_i32 s27, 0x2400
	s_min_u32 s26, s26, s13
	v_add_u32_e32 v51, s27, v182
	s_min_u32 s24, s24, s13
	s_lshl_b32 s92, s26, 13
	s_waitcnt vmcnt(3)
	ds_write_b128 v182, v[138:141]
	s_waitcnt vmcnt(2)
	ds_write_b128 v51, v[142:145] offset:36864
	v_add_f32_e32 v1, v50, v1
	s_add_u32 vcc_lo, s100, s92
	s_addc_u32 vcc_hi, s101, 0
	global_load_dwordx4 v[146:149], v248, vcc
	s_lshl_b32 s92, s24, 7
	s_add_u32 vcc_lo, s98, s92
	s_addc_u32 vcc_hi, s99, 0
	global_load_dwordx4 v[150:153], v249, vcc
	s_add_i32 s27, s25, 1
	s_setprio 1
	v_cvt_pk_bf16_f32 v92, v185, v186
	v_cvt_pk_bf16_f32 v93, v187, v194
	v_cvt_pk_bf16_f32 v94, v195, v196
	v_cvt_pk_bf16_f32 v95, v197, v198
	s_waitcnt lgkmcnt(10)
	s_nop 0
	v_mfma_f32_32x32x16_bf16 v[18:33], v[64:67], v[92:95], v[18:33]
	v_add_f32_e32 v213, v185, v186
	v_add_f32_e32 v213, v213, v187
	v_add_f32_e32 v213, v213, v194
	s_nop 0
	v_mfma_f32_32x32x16_bf16 v[2:17], v[60:63], v[92:95], v[2:17]
	v_cvt_pk_bf16_f32 v64, v199, v200
	v_cvt_pk_bf16_f32 v65, v201, v202
	v_cvt_pk_bf16_f32 v66, v134, v135
	v_cvt_pk_bf16_f32 v67, v136, v137
	v_add_f32_e32 v213, v213, v195
	v_add_f32_e32 v213, v213, v196
	v_add_f32_e32 v213, v213, v197
	v_add_f32_e32 v213, v213, v198
	s_waitcnt lgkmcnt(9)
	v_mfma_f32_32x32x16_bf16 v[18:33], v[68:71], v[64:67], v[18:33]
	v_add_f32_e32 v213, v213, v199
	v_add_f32_e32 v213, v213, v200
	v_add_f32_e32 v213, v213, v201
	v_add_f32_e32 v213, v213, v202
	s_waitcnt lgkmcnt(8)
	v_mfma_f32_32x32x16_bf16 v[2:17], v[72:75], v[64:67], v[2:17]
	v_cvt_pk_bf16_f32 v60, v96, v97
	v_cvt_pk_bf16_f32 v61, v203, v204
	v_cvt_pk_bf16_f32 v62, v130, v131
	v_cvt_pk_bf16_f32 v63, v132, v133
	v_add_f32_e32 v213, v213, v134
	v_add_f32_e32 v213, v213, v135
	v_add_f32_e32 v213, v213, v136
	v_add_f32_e32 v213, v213, v137
	s_waitcnt lgkmcnt(7)
	v_mfma_f32_32x32x16_bf16 v[18:33], v[76:79], v[60:63], v[18:33]
	v_add_f32_e32 v213, v213, v96
	v_add_f32_e32 v213, v213, v97
	v_add_f32_e32 v213, v213, v203
	v_add_f32_e32 v213, v213, v204
	s_waitcnt lgkmcnt(6)
	v_mfma_f32_32x32x16_bf16 v[2:17], v[80:83], v[60:63], v[2:17]
	v_cvt_pk_bf16_f32 v64, v205, v206
	v_cvt_pk_bf16_f32 v65, v207, v208
	v_cvt_pk_bf16_f32 v66, v209, v210
	v_cvt_pk_bf16_f32 v67, v211, v212
	v_add_f32_e32 v213, v213, v130
	v_add_f32_e32 v213, v213, v131
	v_add_f32_e32 v213, v213, v132
	v_add_f32_e32 v213, v213, v133
	s_waitcnt lgkmcnt(5)
	v_mfma_f32_32x32x16_bf16 v[18:33], v[84:87], v[64:67], v[18:33]
	v_add_f32_e32 v213, v213, v205
	v_add_f32_e32 v213, v213, v206
	v_add_f32_e32 v213, v213, v207
	v_add_f32_e32 v213, v213, v208
	s_waitcnt lgkmcnt(4)
	v_mfma_f32_32x32x16_bf16 v[2:17], v[88:91], v[64:67], v[2:17]
	v_add_f32_e32 v213, v213, v209
	v_add_f32_e32 v213, v213, v210
	v_add_f32_e32 v213, v213, v211
	v_add_f32_e32 v213, v213, v212
	s_setprio 0
	ds_read_b128 v[64:67], v165 offset:27680
	ds_read_b128 v[72:75], v165 offset:32288
	s_cmp_lg_u32 s25, 4
	s_cselect_b32 s24, s27, 0
	s_waitcnt lgkmcnt(2)
	v_mfma_f32_32x32x16_bf16 v[130:145], v[240:243], v[158:161], v[34:49]
	v_exp_f32_e32 v185, v114
	v_exp_f32_e32 v186, v115
	v_exp_f32_e32 v187, v116
	v_exp_f32_e32 v194, v117
	v_exp_f32_e32 v195, v118
	v_exp_f32_e32 v196, v119
	v_exp_f32_e32 v197, v120
	v_exp_f32_e32 v198, v121
	s_waitcnt lgkmcnt(1)
	v_mfma_f32_32x32x16_bf16 v[82:97], v[244:247], v[158:161], v[34:49]
	v_exp_f32_e32 v199, v122
	v_exp_f32_e32 v200, v123
	v_exp_f32_e32 v201, v124
	v_exp_f32_e32 v202, v125
	v_exp_f32_e32 v122, v126
	v_exp_f32_e32 v123, v127
	v_exp_f32_e32 v124, v128
	v_exp_f32_e32 v125, v129
	v_mfma_f32_32x32x16_bf16 v[130:145], v[64:67], v[154:157], v[130:145]
	v_exp_f32_e32 v126, v98
	v_exp_f32_e32 v127, v99
	v_exp_f32_e32 v128, v100
	v_exp_f32_e32 v129, v101
	v_exp_f32_e32 v203, v102
	v_exp_f32_e32 v204, v103
	v_exp_f32_e32 v205, v104
	v_exp_f32_e32 v206, v105
	s_waitcnt lgkmcnt(0)
	v_mfma_f32_32x32x16_bf16 v[82:97], v[72:75], v[154:157], v[82:97]
	v_exp_f32_e32 v102, v106
	v_exp_f32_e32 v103, v107
	v_exp_f32_e32 v104, v108
	v_exp_f32_e32 v105, v109
	v_exp_f32_e32 v106, v110
	v_exp_f32_e32 v107, v111
	v_exp_f32_e32 v108, v112
	v_exp_f32_e32 v109, v113
	s_cmp_gt_i32 s24, 2
	s_cselect_b32 s25, -3, 2
	s_add_i32 s25, s25, s24
	s_mulk_i32 s25, 0x2400
	v_add_u32_e32 v50, s25, v182
	s_add_i32 s25, s24, 1
	s_cmp_lg_u32 s24, 4
	s_cselect_b32 s24, s25, 0
	s_add_i32 s25, s23, -5
	s_min_u32 s25, s25, s13
	s_lshl_b32 s92, s25, 13
	s_waitcnt vmcnt(3)
	ds_write_b128 v182, v[52:55] offset:9216
	s_waitcnt vmcnt(2)
	ds_write_b128 v50, v[56:59] offset:36864
	s_add_u32 vcc_lo, s100, s92
	s_addc_u32 vcc_hi, s101, 0
	global_load_dwordx4 v[118:121], v248, vcc
	s_lshl_b32 s92, s26, 7
	s_add_u32 vcc_lo, s98, s92
	s_addc_u32 vcc_hi, s99, 0
	global_load_dwordx4 v[114:117], v249, vcc
	s_mul_i32 s26, s24, 0x2400
	s_add_i32 s27, s26, 0xffffdc00
	s_cmp_lg_u32 s24, 0
	s_cselect_b32 s27, s27, 0x9000
	v_add_u32_e32 v78, s27, v163
	ds_read_b128 v[50:53], v78 offset:36864
	ds_read_b128 v[54:57], v78 offset:36896
	ds_read_b128 v[58:61], v78 offset:41472
	ds_read_b128 v[62:65], v78 offset:41504
	ds_read_b128 v[66:69], v78 offset:36928
	ds_read_b128 v[70:73], v78 offset:36960
	ds_read_b128 v[74:77], v78 offset:41536
	ds_read_b128 v[78:81], v78 offset:41568
	s_setprio 3
	v_cvt_pk_bf16_f32 v98, v185, v186
	v_cvt_pk_bf16_f32 v99, v187, v194
	v_cvt_pk_bf16_f32 v100, v195, v196
	v_cvt_pk_bf16_f32 v101, v197, v198
	s_waitcnt lgkmcnt(7)
	s_nop 0
	v_mfma_f32_32x32x16_bf16 v[18:33], v[50:53], v[98:101], v[18:33]
	v_add_f32_e32 v110, v185, v186
	v_add_f32_e32 v110, v110, v187
	v_add_f32_e32 v110, v110, v194
	s_waitcnt lgkmcnt(5)
	v_mfma_f32_32x32x16_bf16 v[2:17], v[58:61], v[98:101], v[2:17]
	v_cvt_pk_bf16_f32 v50, v199, v200
	v_cvt_pk_bf16_f32 v51, v201, v202
	v_cvt_pk_bf16_f32 v52, v122, v123
	v_cvt_pk_bf16_f32 v53, v124, v125
	v_add_f32_e32 v110, v110, v195
	v_add_f32_e32 v110, v110, v196
	v_add_f32_e32 v110, v110, v197
	v_add_f32_e32 v110, v110, v198
	s_nop 0
	v_mfma_f32_32x32x16_bf16 v[18:33], v[54:57], v[50:53], v[18:33]
	v_add_f32_e32 v110, v110, v199
	v_add_f32_e32 v110, v110, v200
	v_add_f32_e32 v110, v110, v201
	v_add_f32_e32 v110, v110, v202
	s_waitcnt lgkmcnt(4)
	v_mfma_f32_32x32x16_bf16 v[2:17], v[62:65], v[50:53], v[2:17]
	v_cvt_pk_bf16_f32 v54, v126, v127
	v_cvt_pk_bf16_f32 v55, v128, v129
	v_cvt_pk_bf16_f32 v56, v203, v204
	v_cvt_pk_bf16_f32 v57, v205, v206
	v_add_f32_e32 v110, v110, v122
	v_add_f32_e32 v110, v110, v123
	v_add_f32_e32 v110, v110, v124
	v_add_f32_e32 v110, v110, v125
	s_waitcnt lgkmcnt(3)
	v_mfma_f32_32x32x16_bf16 v[18:33], v[66:69], v[54:57], v[18:33]
	v_add_f32_e32 v110, v110, v126
	v_add_f32_e32 v110, v110, v127
	v_add_f32_e32 v110, v110, v128
	v_add_f32_e32 v110, v110, v129
	s_waitcnt lgkmcnt(1)
	v_mfma_f32_32x32x16_bf16 v[2:17], v[74:77], v[54:57], v[2:17]
	v_cvt_pk_bf16_f32 v50, v102, v103
	v_cvt_pk_bf16_f32 v51, v104, v105
	v_cvt_pk_bf16_f32 v52, v106, v107
	v_cvt_pk_bf16_f32 v53, v108, v109
	v_add_f32_e32 v110, v110, v203
	v_add_f32_e32 v110, v110, v204
	v_add_f32_e32 v110, v110, v205
	v_add_f32_e32 v110, v110, v206
	s_nop 0
	v_mfma_f32_32x32x16_bf16 v[18:33], v[70:73], v[50:53], v[18:33]
	v_add_f32_e32 v110, v110, v102
	v_add_f32_e32 v110, v110, v103
	v_add_f32_e32 v110, v110, v104
	v_add_f32_e32 v110, v110, v105
	s_waitcnt lgkmcnt(0)
	v_mfma_f32_32x32x16_bf16 v[2:17], v[78:81], v[50:53], v[2:17]
	v_add_f32_e32 v110, v110, v106
	v_add_f32_e32 v110, v110, v107
	v_add_f32_e32 v110, v110, v108
	v_add_f32_e32 v110, v110, v109
	s_setprio 2
	s_waitcnt lgkmcnt(0)
	s_barrier
	ds_read_b128 v[240:243], v165
	ds_read_b128 v[244:247], v165 offset:4608
	ds_read_b128 v[102:105], v165 offset:32
	ds_read_b128 v[106:109], v165 offset:4640
	v_add_f32_e32 v1, v1, v213
	v_exp_f32_e32 v185, v130
	v_exp_f32_e32 v186, v131
	v_exp_f32_e32 v187, v132
	v_exp_f32_e32 v194, v133
	v_exp_f32_e32 v195, v134
	v_exp_f32_e32 v196, v135
	v_exp_f32_e32 v197, v136
	v_exp_f32_e32 v198, v137
	s_waitcnt lgkmcnt(2)
	v_mfma_f32_32x32x16_bf16 v[66:81], v[240:243], v[158:161], v[34:49]
	v_mfma_f32_32x32x16_bf16 v[50:65], v[244:247], v[158:161], v[34:49]
	v_exp_f32_e32 v134, v138
	v_exp_f32_e32 v135, v139
	v_exp_f32_e32 v136, v140
	v_exp_f32_e32 v137, v141
	v_exp_f32_e32 v138, v142
	v_exp_f32_e32 v139, v143
	v_exp_f32_e32 v140, v144
	v_exp_f32_e32 v141, v145
	s_waitcnt lgkmcnt(1)
	v_mfma_f32_32x32x16_bf16 v[66:81], v[102:105], v[154:157], v[66:81]
	v_exp_f32_e32 v142, v82
	v_exp_f32_e32 v143, v83
	v_exp_f32_e32 v144, v84
	v_exp_f32_e32 v145, v85
	v_exp_f32_e32 v199, v86
	v_exp_f32_e32 v200, v87
	v_exp_f32_e32 v201, v88
	v_exp_f32_e32 v202, v89
	s_waitcnt lgkmcnt(0)
	v_mfma_f32_32x32x16_bf16 v[50:65], v[106:109], v[154:157], v[50:65]
	v_exp_f32_e32 v203, v90
	v_exp_f32_e32 v204, v91
	v_exp_f32_e32 v205, v92
	v_exp_f32_e32 v206, v93
	v_exp_f32_e32 v207, v94
	v_exp_f32_e32 v208, v95
	v_exp_f32_e32 v209, v96
	v_exp_f32_e32 v210, v97
	v_add_f32_e32 v1, v1, v110
	v_add_u32_e32 v111, s26, v163
	ds_read_b128 v[82:85], v111 offset:41472
	ds_read_b128 v[86:89], v111 offset:36864
	ds_read_b128 v[90:93], v111 offset:36896
	ds_read_b128 v[94:97], v111 offset:41504
	ds_read_b128 v[98:101], v111 offset:36928
	ds_read_b128 v[102:105], v111 offset:41536
	ds_read_b128 v[106:109], v111 offset:36960
	ds_read_b128 v[110:113], v111 offset:41568
	ds_read_b128 v[240:243], v165 offset:9216
	ds_read_b128 v[244:247], v165 offset:13824
	s_cmp_gt_i32 s24, 2
	s_cselect_b32 s27, -3, 2
	s_add_i32 s27, s27, s24
	s_mulk_i32 s27, 0x2400
	v_add_u32_e32 v250, s27, v182
	s_mov_b32 s27, 0x18950000
	s_waitcnt vmcnt(3)
	ds_write_b128 v182, v[146:149] offset:18432
	s_waitcnt vmcnt(2)
	ds_write_b128 v250, v[150:153] offset:36864
	s_add_i32 s92, s23, -4
	s_lshl_b32 s92, s92, 13
	s_add_u32 vcc_lo, s100, s92
	s_addc_u32 vcc_hi, s101, 0
	global_load_dwordx4 v[126:129], v248, vcc
	s_lshl_b32 s92, s25, 7
	s_add_u32 vcc_lo, s98, s92
	s_addc_u32 vcc_hi, s99, 0
	global_load_dwordx4 v[122:125], v249, vcc
	s_add_i32 s26, s24, 1
	s_setprio 1
	v_cvt_pk_bf16_f32 v130, v185, v186
	v_cvt_pk_bf16_f32 v131, v187, v194
	v_cvt_pk_bf16_f32 v132, v195, v196
	v_cvt_pk_bf16_f32 v133, v197, v198
	s_waitcnt lgkmcnt(10)
	s_nop 0
	v_mfma_f32_32x32x16_bf16 v[18:33], v[86:89], v[130:133], v[18:33]
	v_add_f32_e32 v146, v185, v186
	v_add_f32_e32 v146, v146, v187
	v_add_f32_e32 v146, v146, v194
	s_nop 0
	v_mfma_f32_32x32x16_bf16 v[2:17], v[82:85], v[130:133], v[2:17]
	v_cvt_pk_bf16_f32 v86, v134, v135
	v_cvt_pk_bf16_f32 v87, v136, v137
	v_cvt_pk_bf16_f32 v88, v138, v139
	v_cvt_pk_bf16_f32 v89, v140, v141
	v_add_f32_e32 v146, v146, v195
	v_add_f32_e32 v146, v146, v196
	v_add_f32_e32 v146, v146, v197
	v_add_f32_e32 v146, v146, v198
	s_waitcnt lgkmcnt(9)
	v_mfma_f32_32x32x16_bf16 v[18:33], v[90:93], v[86:89], v[18:33]
	v_add_f32_e32 v146, v146, v134
	v_add_f32_e32 v146, v146, v135
	v_add_f32_e32 v146, v146, v136
	v_add_f32_e32 v146, v146, v137
	s_waitcnt lgkmcnt(8)
	v_mfma_f32_32x32x16_bf16 v[2:17], v[94:97], v[86:89], v[2:17]
	v_cvt_pk_bf16_f32 v82, v142, v143
	v_cvt_pk_bf16_f32 v83, v144, v145
	v_cvt_pk_bf16_f32 v84, v199, v200
	v_cvt_pk_bf16_f32 v85, v201, v202
	v_add_f32_e32 v146, v146, v138
	v_add_f32_e32 v146, v146, v139
	v_add_f32_e32 v146, v146, v140
	v_add_f32_e32 v146, v146, v141
	s_waitcnt lgkmcnt(7)
	v_mfma_f32_32x32x16_bf16 v[18:33], v[98:101], v[82:85], v[18:33]
	v_add_f32_e32 v146, v146, v142
	v_add_f32_e32 v146, v146, v143
	v_add_f32_e32 v146, v146, v144
	v_add_f32_e32 v146, v146, v145
	s_waitcnt lgkmcnt(6)
	v_mfma_f32_32x32x16_bf16 v[2:17], v[102:105], v[82:85], v[2:17]
	v_cvt_pk_bf16_f32 v86, v203, v204
	v_cvt_pk_bf16_f32 v87, v205, v206
	v_cvt_pk_bf16_f32 v88, v207, v208
	v_cvt_pk_bf16_f32 v89, v209, v210
	v_add_f32_e32 v146, v146, v199
	v_add_f32_e32 v146, v146, v200
	v_add_f32_e32 v146, v146, v201
	v_add_f32_e32 v146, v146, v202
	s_waitcnt lgkmcnt(5)
	v_mfma_f32_32x32x16_bf16 v[18:33], v[106:109], v[86:89], v[18:33]
	v_add_f32_e32 v146, v146, v203
	v_add_f32_e32 v146, v146, v204
	v_add_f32_e32 v146, v146, v205
	v_add_f32_e32 v146, v146, v206
	s_waitcnt lgkmcnt(4)
	v_mfma_f32_32x32x16_bf16 v[2:17], v[110:113], v[86:89], v[2:17]
	v_add_f32_e32 v146, v146, v207
	v_add_f32_e32 v146, v146, v208
	v_add_f32_e32 v146, v146, v209
	v_add_f32_e32 v146, v146, v210
	s_setprio 0
	ds_read_b128 v[130:133], v165 offset:9248
	ds_read_b128 v[138:141], v165 offset:13856
	s_cmp_lg_u32 s24, 4
	s_cselect_b32 s24, s26, 0
	s_waitcnt lgkmcnt(2)
	v_mfma_f32_32x32x16_bf16 v[98:113], v[240:243], v[158:161], v[34:49]
	v_exp_f32_e32 v142, v66
	v_exp_f32_e32 v143, v67
	v_exp_f32_e32 v144, v68
	v_exp_f32_e32 v145, v69
	v_exp_f32_e32 v147, v70
	v_exp_f32_e32 v148, v71
	v_exp_f32_e32 v149, v72
	v_exp_f32_e32 v150, v73
	s_waitcnt lgkmcnt(1)
	v_mfma_f32_32x32x16_bf16 v[82:97], v[244:247], v[158:161], v[34:49]
	v_exp_f32_e32 v151, v74
	v_exp_f32_e32 v152, v75
	v_exp_f32_e32 v153, v76
	v_exp_f32_e32 v178, v77
	v_exp_f32_e32 v134, v78
	v_exp_f32_e32 v135, v79
	v_exp_f32_e32 v136, v80
	v_exp_f32_e32 v137, v81
	v_mfma_f32_32x32x16_bf16 v[98:113], v[130:133], v[154:157], v[98:113]
	v_exp_f32_e32 v179, v50
	v_exp_f32_e32 v185, v51
	v_exp_f32_e32 v186, v52
	v_exp_f32_e32 v187, v53
	v_exp_f32_e32 v194, v54
	v_exp_f32_e32 v195, v55
	v_exp_f32_e32 v196, v56
	v_exp_f32_e32 v197, v57
	s_waitcnt lgkmcnt(0)
	v_mfma_f32_32x32x16_bf16 v[82:97], v[138:141], v[154:157], v[82:97]
	v_exp_f32_e32 v198, v58
	v_exp_f32_e32 v199, v59
	v_exp_f32_e32 v200, v60
	v_exp_f32_e32 v201, v61
	v_exp_f32_e32 v138, v62
	v_exp_f32_e32 v139, v63
	v_exp_f32_e32 v140, v64
	v_exp_f32_e32 v141, v65
	s_cmp_gt_i32 s24, 2
	s_cselect_b32 s25, -3, 2
	s_add_i32 s25, s25, s24
	s_mulk_i32 s25, 0x2400
	v_add_u32_e32 v50, s25, v182
	s_add_i32 s25, s24, 1
	s_cmp_lg_u32 s24, 4
	s_cselect_b32 s25, s25, 0
	s_add_i32 s24, s23, -3
	s_min_u32 s26, s24, s13
	s_lshl_b32 s92, s26, 13
	s_waitcnt vmcnt(3)
	ds_write_b128 v182, v[118:121] offset:27648
	s_waitcnt vmcnt(2)
	ds_write_b128 v50, v[114:117] offset:36864
	s_add_u32 vcc_lo, s100, s92
	s_addc_u32 vcc_hi, s101, 0
	global_load_dwordx4 v[118:121], v248, vcc
	s_add_i32 s92, s23, -4
	s_lshl_b32 s92, s92, 7
	s_add_u32 vcc_lo, s98, s92
	s_addc_u32 vcc_hi, s99, 0
	global_load_dwordx4 v[114:117], v249, vcc
	s_mul_i32 s27, s25, 0x2400
	s_add_i32 s28, s27, 0xffffdc00
	s_cmp_lg_u32 s25, 0
	s_cselect_b32 s28, s28, 0x9000
	v_add_u32_e32 v78, s28, v163
	ds_read_b128 v[50:53], v78 offset:36864
	ds_read_b128 v[54:57], v78 offset:36896
	ds_read_b128 v[58:61], v78 offset:41472
	ds_read_b128 v[62:65], v78 offset:41504
	ds_read_b128 v[66:69], v78 offset:36928
	ds_read_b128 v[70:73], v78 offset:36960
	ds_read_b128 v[74:77], v78 offset:41536
	ds_read_b128 v[78:81], v78 offset:41568
	s_setprio 3
	v_cvt_pk_bf16_f32 v130, v142, v143
	v_cvt_pk_bf16_f32 v131, v144, v145
	v_cvt_pk_bf16_f32 v132, v147, v148
	v_cvt_pk_bf16_f32 v133, v149, v150
	s_waitcnt lgkmcnt(7)
	s_nop 0
	v_mfma_f32_32x32x16_bf16 v[18:33], v[50:53], v[130:133], v[18:33]
	v_add_f32_e32 v176, v142, v143
	v_add_f32_e32 v176, v176, v144
	v_add_f32_e32 v176, v176, v145
	s_waitcnt lgkmcnt(5)
	v_mfma_f32_32x32x16_bf16 v[2:17], v[58:61], v[130:133], v[2:17]
	v_cvt_pk_bf16_f32 v50, v151, v152
	v_cvt_pk_bf16_f32 v51, v153, v178
	v_cvt_pk_bf16_f32 v52, v134, v135
	v_cvt_pk_bf16_f32 v53, v136, v137
	v_add_f32_e32 v176, v176, v147
	v_add_f32_e32 v176, v176, v148
	v_add_f32_e32 v176, v176, v149
	v_add_f32_e32 v176, v176, v150
	s_nop 0
	v_mfma_f32_32x32x16_bf16 v[18:33], v[54:57], v[50:53], v[18:33]
	v_add_f32_e32 v176, v176, v151
	v_add_f32_e32 v176, v176, v152
	v_add_f32_e32 v176, v176, v153
	v_add_f32_e32 v176, v176, v178
	s_waitcnt lgkmcnt(4)
	v_mfma_f32_32x32x16_bf16 v[2:17], v[62:65], v[50:53], v[2:17]
	v_cvt_pk_bf16_f32 v54, v179, v185
	v_cvt_pk_bf16_f32 v55, v186, v187
	v_cvt_pk_bf16_f32 v56, v194, v195
	v_cvt_pk_bf16_f32 v57, v196, v197
	v_add_f32_e32 v176, v176, v134
	v_add_f32_e32 v176, v176, v135
	v_add_f32_e32 v176, v176, v136
	v_add_f32_e32 v176, v176, v137
	s_waitcnt lgkmcnt(3)
	v_mfma_f32_32x32x16_bf16 v[18:33], v[66:69], v[54:57], v[18:33]
	v_add_f32_e32 v176, v176, v179
	v_add_f32_e32 v176, v176, v185
	v_add_f32_e32 v176, v176, v186
	v_add_f32_e32 v176, v176, v187
	s_waitcnt lgkmcnt(1)
	v_mfma_f32_32x32x16_bf16 v[2:17], v[74:77], v[54:57], v[2:17]
	v_cvt_pk_bf16_f32 v50, v198, v199
	v_cvt_pk_bf16_f32 v51, v200, v201
	v_cvt_pk_bf16_f32 v52, v138, v139
	v_cvt_pk_bf16_f32 v53, v140, v141
	v_add_f32_e32 v176, v176, v194
	v_add_f32_e32 v176, v176, v195
	v_add_f32_e32 v176, v176, v196
	v_add_f32_e32 v176, v176, v197
	s_nop 0
	v_mfma_f32_32x32x16_bf16 v[18:33], v[70:73], v[50:53], v[18:33]
	v_add_f32_e32 v176, v176, v198
	v_add_f32_e32 v176, v176, v199
	v_add_f32_e32 v176, v176, v200
	v_add_f32_e32 v176, v176, v201
	s_waitcnt lgkmcnt(0)
	v_mfma_f32_32x32x16_bf16 v[2:17], v[78:81], v[50:53], v[2:17]
	v_add_f32_e32 v176, v176, v138
	v_add_f32_e32 v176, v176, v139
	v_add_f32_e32 v176, v176, v140
	v_add_f32_e32 v176, v176, v141
	s_setprio 2
	s_waitcnt lgkmcnt(0)
	s_barrier
	ds_read_b128 v[240:243], v165 offset:18432
	ds_read_b128 v[244:247], v165 offset:23040
	ds_read_b128 v[134:137], v165 offset:18464
	ds_read_b128 v[138:141], v165 offset:23072
	v_add_f32_e32 v1, v1, v146
	v_exp_f32_e32 v142, v98
	v_exp_f32_e32 v143, v99
	v_exp_f32_e32 v144, v100
	v_exp_f32_e32 v145, v101
	v_exp_f32_e32 v146, v102
	v_exp_f32_e32 v147, v103
	v_exp_f32_e32 v148, v104
	v_exp_f32_e32 v149, v105
	s_waitcnt lgkmcnt(2)
	v_mfma_f32_32x32x16_bf16 v[66:81], v[240:243], v[158:161], v[34:49]
	v_mfma_f32_32x32x16_bf16 v[50:65], v[244:247], v[158:161], v[34:49]
	v_exp_f32_e32 v150, v106
	v_exp_f32_e32 v151, v107
	v_exp_f32_e32 v152, v108
	v_exp_f32_e32 v153, v109
	v_exp_f32_e32 v177, v110
	v_exp_f32_e32 v178, v111
	v_exp_f32_e32 v179, v112
	v_exp_f32_e32 v185, v113
	s_waitcnt lgkmcnt(1)
	v_mfma_f32_32x32x16_bf16 v[66:81], v[134:137], v[154:157], v[66:81]
	v_exp_f32_e32 v186, v82
	v_exp_f32_e32 v187, v83
	v_exp_f32_e32 v194, v84
	v_exp_f32_e32 v195, v85
	v_exp_f32_e32 v134, v86
	v_exp_f32_e32 v135, v87
	v_exp_f32_e32 v136, v88
	v_exp_f32_e32 v137, v89
	s_waitcnt lgkmcnt(0)
	v_mfma_f32_32x32x16_bf16 v[50:65], v[138:141], v[154:157], v[50:65]
	v_exp_f32_e32 v196, v90
	v_exp_f32_e32 v197, v91
	v_exp_f32_e32 v198, v92
	v_exp_f32_e32 v199, v93
	v_exp_f32_e32 v138, v94
	v_exp_f32_e32 v139, v95
	v_exp_f32_e32 v140, v96
	v_exp_f32_e32 v141, v97
	s_cmp_gt_i32 s25, 2
	s_cselect_b32 s28, -3, 2
	s_waitcnt vmcnt(3)
	ds_write_b128 v182, v[126:129]
	s_add_i32 s28, s28, s25
	v_add_u32_e32 v126, s27, v163
	s_add_i32 s27, s23, -2
	s_mulk_i32 s28, 0x2400
	s_min_u32 s27, s27, s13
	v_add_u32_e32 v82, s28, v182
	s_lshl_b32 s92, s27, 13
	s_waitcnt vmcnt(2)
	ds_write_b128 v82, v[122:125] offset:36864
	ds_read_b128 v[82:85], v126 offset:41472
	ds_read_b128 v[86:89], v126 offset:36864
	ds_read_b128 v[90:93], v126 offset:36896
	ds_read_b128 v[94:97], v126 offset:41504
	ds_read_b128 v[106:109], v126 offset:36928
	ds_read_b128 v[110:113], v126 offset:41536
	ds_read_b128 v[122:125], v126 offset:36960
	ds_read_b128 v[126:129], v126 offset:41568
	ds_read_b128 v[240:243], v165 offset:27648
	ds_read_b128 v[244:247], v165 offset:32256
	s_add_u32 vcc_lo, s100, s92
	s_addc_u32 vcc_hi, s101, 0
	global_load_dwordx4 v[98:101], v248, vcc
	s_lshl_b32 s92, s26, 7
	s_add_u32 vcc_lo, s98, s92
	s_addc_u32 vcc_hi, s99, 0
	global_load_dwordx4 v[102:105], v249, vcc
	v_add_f32_e32 v1, v1, v176
	s_add_i32 s28, s25, 1
	s_setprio 1
	v_cvt_pk_bf16_f32 v130, v142, v143
	v_cvt_pk_bf16_f32 v131, v144, v145
	v_cvt_pk_bf16_f32 v132, v146, v147
	v_cvt_pk_bf16_f32 v133, v148, v149
	s_waitcnt lgkmcnt(8)
	s_nop 0
	v_mfma_f32_32x32x16_bf16 v[18:33], v[86:89], v[130:133], v[18:33]
	v_add_f32_e32 v176, v142, v143
	v_add_f32_e32 v176, v176, v144
	v_add_f32_e32 v176, v176, v145
	s_nop 0
	v_mfma_f32_32x32x16_bf16 v[2:17], v[82:85], v[130:133], v[2:17]
	v_cvt_pk_bf16_f32 v86, v150, v151
	v_cvt_pk_bf16_f32 v87, v152, v153
	v_cvt_pk_bf16_f32 v88, v177, v178
	v_cvt_pk_bf16_f32 v89, v179, v185
	v_add_f32_e32 v176, v176, v146
	v_add_f32_e32 v176, v176, v147
	v_add_f32_e32 v176, v176, v148
	v_add_f32_e32 v176, v176, v149
	s_waitcnt lgkmcnt(7)
	v_mfma_f32_32x32x16_bf16 v[18:33], v[90:93], v[86:89], v[18:33]
	v_add_f32_e32 v176, v176, v150
	v_add_f32_e32 v176, v176, v151
	v_add_f32_e32 v176, v176, v152
	v_add_f32_e32 v176, v176, v153
	s_waitcnt lgkmcnt(6)
	v_mfma_f32_32x32x16_bf16 v[2:17], v[94:97], v[86:89], v[2:17]
	v_cvt_pk_bf16_f32 v82, v186, v187
	v_cvt_pk_bf16_f32 v83, v194, v195
	v_cvt_pk_bf16_f32 v84, v134, v135
	v_cvt_pk_bf16_f32 v85, v136, v137
	v_add_f32_e32 v176, v176, v177
	v_add_f32_e32 v176, v176, v178
	v_add_f32_e32 v176, v176, v179
	v_add_f32_e32 v176, v176, v185
	s_waitcnt lgkmcnt(5)
	v_mfma_f32_32x32x16_bf16 v[18:33], v[106:109], v[82:85], v[18:33]
	v_add_f32_e32 v176, v176, v186
	v_add_f32_e32 v176, v176, v187
	v_add_f32_e32 v176, v176, v194
	v_add_f32_e32 v176, v176, v195
	s_waitcnt lgkmcnt(4)
	v_mfma_f32_32x32x16_bf16 v[2:17], v[110:113], v[82:85], v[2:17]
	v_cvt_pk_bf16_f32 v86, v196, v197
	v_cvt_pk_bf16_f32 v87, v198, v199
	v_cvt_pk_bf16_f32 v88, v138, v139
	v_cvt_pk_bf16_f32 v89, v140, v141
	v_add_f32_e32 v176, v176, v134
	v_add_f32_e32 v176, v176, v135
	v_add_f32_e32 v176, v176, v136
	v_add_f32_e32 v176, v176, v137
	s_waitcnt lgkmcnt(3)
	v_mfma_f32_32x32x16_bf16 v[18:33], v[122:125], v[86:89], v[18:33]
	v_add_f32_e32 v176, v176, v196
	v_add_f32_e32 v176, v176, v197
	v_add_f32_e32 v176, v176, v198
	v_add_f32_e32 v176, v176, v199
	s_waitcnt lgkmcnt(2)
	v_mfma_f32_32x32x16_bf16 v[2:17], v[126:129], v[86:89], v[2:17]
	v_add_f32_e32 v176, v176, v138
	v_add_f32_e32 v176, v176, v139
	v_add_f32_e32 v176, v176, v140
	v_add_f32_e32 v176, v176, v141
	s_setprio 0
	ds_read_b128 v[106:109], v165 offset:27680
	ds_read_b128 v[122:125], v165 offset:32288
	s_cmp_lg_u32 s25, 4
	s_cselect_b32 s25, s28, 0
	s_waitcnt lgkmcnt(2)
	v_mfma_f32_32x32x16_bf16 v[138:153], v[240:243], v[158:161], v[34:49]
	v_exp_f32_e32 v126, v66
	v_exp_f32_e32 v127, v67
	v_exp_f32_e32 v128, v68
	v_exp_f32_e32 v129, v69
	v_exp_f32_e32 v130, v70
	v_exp_f32_e32 v131, v71
	v_exp_f32_e32 v132, v72
	v_exp_f32_e32 v133, v73
	s_waitcnt lgkmcnt(1)
	v_mfma_f32_32x32x16_bf16 v[82:97], v[244:247], v[158:161], v[34:49]
	v_exp_f32_e32 v134, v74
	v_exp_f32_e32 v135, v75
	v_exp_f32_e32 v136, v76
	v_exp_f32_e32 v137, v77
	v_exp_f32_e32 v177, v78
	v_exp_f32_e32 v178, v79
	v_exp_f32_e32 v179, v80
	v_exp_f32_e32 v185, v81
	v_mfma_f32_32x32x16_bf16 v[138:153], v[106:109], v[154:157], v[138:153]
	v_exp_f32_e32 v80, v50
	v_exp_f32_e32 v81, v51
	v_exp_f32_e32 v186, v52
	v_exp_f32_e32 v187, v53
	v_exp_f32_e32 v194, v54
	v_exp_f32_e32 v195, v55
	v_exp_f32_e32 v196, v56
	v_exp_f32_e32 v197, v57
	s_waitcnt lgkmcnt(0)
	v_mfma_f32_32x32x16_bf16 v[82:97], v[122:125], v[154:157], v[82:97]
	v_exp_f32_e32 v198, v58
	v_exp_f32_e32 v199, v59
	v_exp_f32_e32 v200, v60
	v_exp_f32_e32 v201, v61
	v_exp_f32_e32 v122, v62
	v_exp_f32_e32 v123, v63
	v_exp_f32_e32 v124, v64
	v_exp_f32_e32 v125, v65
	s_cmp_gt_i32 s25, 2
	s_cselect_b32 s26, -3, 2
	s_add_i32 s26, s26, s25
	s_mulk_i32 s26, 0x2400
	v_add_u32_e32 v50, s26, v182
	s_add_i32 s26, s25, 1
	s_cmp_lg_u32 s25, 4
	s_cselect_b32 s25, s26, 0
	s_add_i32 s26, s23, -1
	s_min_u32 s26, s26, s13
	s_lshl_b32 s92, s26, 13
	s_waitcnt vmcnt(3)
	ds_write_b128 v182, v[118:121] offset:9216
	s_waitcnt vmcnt(2)
	ds_write_b128 v50, v[114:117] offset:36864
	s_add_u32 vcc_lo, s100, s92
	s_addc_u32 vcc_hi, s101, 0
	global_load_dwordx4 v[56:59], v248, vcc
	s_lshl_b32 s92, s27, 7
	s_add_u32 vcc_lo, s98, s92
	s_addc_u32 vcc_hi, s99, 0
	global_load_dwordx4 v[52:55], v249, vcc
	s_nop 0
	s_mul_i32 s27, s25, 0x2400
	s_add_i32 s28, s27, 0xffffdc00
	s_cmp_lg_u32 s25, 0
	s_cselect_b32 s28, s28, 0x9000
	v_add_u32_e32 v50, s28, v163
	ds_read_b128 v[60:63], v50 offset:36864
	ds_read_b128 v[64:67], v50 offset:36896
	ds_read_b128 v[68:71], v50 offset:41472
	ds_read_b128 v[72:75], v50 offset:41504
	ds_read_b128 v[76:79], v50 offset:36928
	ds_read_b128 v[106:109], v50 offset:36960
	ds_read_b128 v[110:113], v50 offset:41536
	ds_read_b128 v[114:117], v50 offset:41568
	s_setprio 3
	v_cvt_pk_bf16_f32 v118, v126, v127
	v_cvt_pk_bf16_f32 v119, v128, v129
	v_cvt_pk_bf16_f32 v120, v130, v131
	v_cvt_pk_bf16_f32 v121, v132, v133
	s_waitcnt lgkmcnt(7)
	s_nop 0
	v_mfma_f32_32x32x16_bf16 v[18:33], v[60:63], v[118:121], v[18:33]
	v_add_f32_e32 v50, v126, v127
	v_add_f32_e32 v50, v50, v128
	v_add_f32_e32 v50, v50, v129
	s_waitcnt lgkmcnt(5)
	v_mfma_f32_32x32x16_bf16 v[2:17], v[68:71], v[118:121], v[2:17]
	v_cvt_pk_bf16_f32 v60, v134, v135
	v_cvt_pk_bf16_f32 v61, v136, v137
	v_cvt_pk_bf16_f32 v62, v177, v178
	v_cvt_pk_bf16_f32 v63, v179, v185
	v_add_f32_e32 v50, v50, v130
	v_add_f32_e32 v50, v50, v131
	v_add_f32_e32 v50, v50, v132
	v_add_f32_e32 v50, v50, v133
	s_nop 0
	v_mfma_f32_32x32x16_bf16 v[18:33], v[64:67], v[60:63], v[18:33]
	v_add_f32_e32 v50, v50, v134
	v_add_f32_e32 v50, v50, v135
	v_add_f32_e32 v50, v50, v136
	v_add_f32_e32 v50, v50, v137
	s_waitcnt lgkmcnt(4)
	v_mfma_f32_32x32x16_bf16 v[2:17], v[72:75], v[60:63], v[2:17]
	v_cvt_pk_bf16_f32 v64, v80, v81
	v_cvt_pk_bf16_f32 v65, v186, v187
	v_cvt_pk_bf16_f32 v66, v194, v195
	v_cvt_pk_bf16_f32 v67, v196, v197
	v_add_f32_e32 v50, v50, v177
	v_add_f32_e32 v50, v50, v178
	v_add_f32_e32 v50, v50, v179
	v_add_f32_e32 v50, v50, v185
	s_waitcnt lgkmcnt(3)
	v_mfma_f32_32x32x16_bf16 v[18:33], v[76:79], v[64:67], v[18:33]
	v_add_f32_e32 v50, v50, v80
	v_add_f32_e32 v50, v50, v81
	v_add_f32_e32 v50, v50, v186
	v_add_f32_e32 v50, v50, v187
	s_waitcnt lgkmcnt(1)
	v_mfma_f32_32x32x16_bf16 v[2:17], v[110:113], v[64:67], v[2:17]
	v_cvt_pk_bf16_f32 v60, v198, v199
	v_cvt_pk_bf16_f32 v61, v200, v201
	v_cvt_pk_bf16_f32 v62, v122, v123
	v_cvt_pk_bf16_f32 v63, v124, v125
	v_add_f32_e32 v50, v50, v194
	v_add_f32_e32 v50, v50, v195
	v_add_f32_e32 v50, v50, v196
	v_add_f32_e32 v50, v50, v197
	s_nop 0
	v_mfma_f32_32x32x16_bf16 v[18:33], v[106:109], v[60:63], v[18:33]
	v_add_f32_e32 v50, v50, v198
	v_add_f32_e32 v50, v50, v199
	v_add_f32_e32 v50, v50, v200
	v_add_f32_e32 v50, v50, v201
	s_waitcnt lgkmcnt(0)
	v_mfma_f32_32x32x16_bf16 v[2:17], v[114:117], v[60:63], v[2:17]
	v_add_f32_e32 v50, v50, v122
	v_add_f32_e32 v50, v50, v123
	v_add_f32_e32 v50, v50, v124
	v_add_f32_e32 v50, v50, v125
	s_setprio 2
	s_waitcnt lgkmcnt(0)
	s_barrier
	ds_read_b128 v[240:243], v165
	ds_read_b128 v[244:247], v165 offset:4608
	ds_read_b128 v[68:71], v165 offset:32
	ds_read_b128 v[72:75], v165 offset:4640
	v_add_f32_e32 v1, v1, v176
	v_exp_f32_e32 v176, v138
	v_exp_f32_e32 v177, v139
	v_exp_f32_e32 v178, v140
	v_exp_f32_e32 v179, v141
	v_exp_f32_e32 v185, v142
	v_exp_f32_e32 v186, v143
	v_exp_f32_e32 v187, v144
	v_exp_f32_e32 v194, v145
	s_waitcnt lgkmcnt(2)
	v_mfma_f32_32x32x16_bf16 v[122:137], v[240:243], v[158:161], v[34:49]
	v_mfma_f32_32x32x16_bf16 v[106:121], v[244:247], v[158:161], v[34:49]
	v_exp_f32_e32 v195, v146
	v_exp_f32_e32 v196, v147
	v_exp_f32_e32 v197, v148
	v_exp_f32_e32 v198, v149
	v_exp_f32_e32 v146, v150
	v_exp_f32_e32 v147, v151
	v_exp_f32_e32 v148, v152
	v_exp_f32_e32 v149, v153
	s_waitcnt lgkmcnt(1)
	v_mfma_f32_32x32x16_bf16 v[122:137], v[68:71], v[154:157], v[122:137]
	v_exp_f32_e32 v150, v82
	v_exp_f32_e32 v151, v83
	v_exp_f32_e32 v152, v84
	v_exp_f32_e32 v153, v85
	v_exp_f32_e32 v199, v86
	v_exp_f32_e32 v200, v87
	v_exp_f32_e32 v201, v88
	v_exp_f32_e32 v202, v89
	s_waitcnt lgkmcnt(0)
	v_mfma_f32_32x32x16_bf16 v[106:121], v[72:75], v[154:157], v[106:121]
	v_exp_f32_e32 v203, v90
	v_exp_f32_e32 v204, v91
	v_exp_f32_e32 v205, v92
	v_exp_f32_e32 v206, v93
	v_exp_f32_e32 v207, v94
	v_exp_f32_e32 v208, v95
	v_exp_f32_e32 v209, v96
	v_exp_f32_e32 v210, v97
	v_add_u32_e32 v88, s27, v163
	ds_read_b128 v[60:63], v88 offset:41472
	ds_read_b128 v[64:67], v88 offset:36864
	ds_read_b128 v[68:71], v88 offset:36896
	ds_read_b128 v[72:75], v88 offset:41504
	ds_read_b128 v[76:79], v88 offset:36928
	ds_read_b128 v[80:83], v88 offset:41536
	ds_read_b128 v[84:87], v88 offset:36960
	ds_read_b128 v[88:91], v88 offset:41568
	ds_read_b128 v[240:243], v165 offset:9216
	ds_read_b128 v[244:247], v165 offset:13824
	s_cmp_gt_i32 s25, 2
	s_cselect_b32 s28, -3, 2
	s_add_i32 s28, s28, s25
	s_mulk_i32 s28, 0x2400
	s_min_u32 s27, s23, s13
	v_add_u32_e32 v51, s28, v182
	s_lshl_b32 s92, s27, 13
	s_waitcnt vmcnt(3)
	ds_write_b128 v182, v[98:101] offset:18432
	s_waitcnt vmcnt(2)
	ds_write_b128 v51, v[102:105] offset:36864
	v_add_f32_e32 v1, v1, v50
	s_add_u32 vcc_lo, s100, s92
	s_addc_u32 vcc_hi, s101, 0
	global_load_dwordx4 v[138:141], v248, vcc
	s_lshl_b32 s92, s26, 7
	s_add_u32 vcc_lo, s98, s92
	s_addc_u32 vcc_hi, s99, 0
	global_load_dwordx4 v[142:145], v249, vcc
	s_setprio 1
	v_mov_b32_e32 v51, v122
	v_cvt_pk_bf16_f32 v92, v176, v177
	v_cvt_pk_bf16_f32 v93, v178, v179
	v_cvt_pk_bf16_f32 v94, v185, v186
	v_cvt_pk_bf16_f32 v95, v187, v194
	s_waitcnt lgkmcnt(10)
	s_nop 0
	v_mfma_f32_32x32x16_bf16 v[18:33], v[64:67], v[92:95], v[18:33]
	v_max3_f32 v51, v51, v123, v124
	v_max3_f32 v51, v51, v125, v126
	v_add_f32_e32 v50, v176, v177
	v_add_f32_e32 v50, v50, v178
	v_add_f32_e32 v50, v50, v179
	s_nop 0
	v_mfma_f32_32x32x16_bf16 v[2:17], v[60:63], v[92:95], v[2:17]
	v_cvt_pk_bf16_f32 v64, v195, v196
	v_cvt_pk_bf16_f32 v65, v197, v198
	v_cvt_pk_bf16_f32 v66, v146, v147
	v_cvt_pk_bf16_f32 v67, v148, v149
	v_max3_f32 v51, v51, v127, v128
	v_max3_f32 v51, v51, v129, v130
	v_add_f32_e32 v50, v50, v185
	v_add_f32_e32 v50, v50, v186
	v_add_f32_e32 v50, v50, v187
	v_add_f32_e32 v50, v50, v194
	s_waitcnt lgkmcnt(9)
	v_mfma_f32_32x32x16_bf16 v[18:33], v[68:71], v[64:67], v[18:33]
	v_max3_f32 v51, v51, v131, v132
	v_max3_f32 v51, v51, v133, v134
	v_add_f32_e32 v50, v50, v195
	v_add_f32_e32 v50, v50, v196
	v_add_f32_e32 v50, v50, v197
	v_add_f32_e32 v50, v50, v198
	s_waitcnt lgkmcnt(8)
	v_mfma_f32_32x32x16_bf16 v[2:17], v[72:75], v[64:67], v[2:17]
	v_cvt_pk_bf16_f32 v60, v150, v151
	v_cvt_pk_bf16_f32 v61, v152, v153
	v_cvt_pk_bf16_f32 v62, v199, v200
	v_cvt_pk_bf16_f32 v63, v201, v202
	v_max3_f32 v51, v51, v135, v136
	v_max3_f32 v51, v51, v137, v106
	v_add_f32_e32 v50, v50, v146
	v_add_f32_e32 v50, v50, v147
	v_add_f32_e32 v50, v50, v148
	v_add_f32_e32 v50, v50, v149
	s_waitcnt lgkmcnt(7)
	v_mfma_f32_32x32x16_bf16 v[18:33], v[76:79], v[60:63], v[18:33]
	v_max3_f32 v51, v51, v107, v108
	v_max3_f32 v51, v51, v109, v110
	v_add_f32_e32 v50, v50, v150
	v_add_f32_e32 v50, v50, v151
	v_add_f32_e32 v50, v50, v152
	v_add_f32_e32 v50, v50, v153
	s_waitcnt lgkmcnt(6)
	v_mfma_f32_32x32x16_bf16 v[2:17], v[80:83], v[60:63], v[2:17]
	v_cvt_pk_bf16_f32 v64, v203, v204
	v_cvt_pk_bf16_f32 v65, v205, v206
	v_cvt_pk_bf16_f32 v66, v207, v208
	v_cvt_pk_bf16_f32 v67, v209, v210
	v_max3_f32 v51, v51, v111, v112
	v_max3_f32 v51, v51, v113, v114
	v_add_f32_e32 v50, v50, v199
	v_add_f32_e32 v50, v50, v200
	v_add_f32_e32 v50, v50, v201
	v_add_f32_e32 v50, v50, v202
	s_waitcnt lgkmcnt(5)
	v_mfma_f32_32x32x16_bf16 v[18:33], v[84:87], v[64:67], v[18:33]
	v_max3_f32 v51, v51, v115, v116
	v_max3_f32 v51, v51, v117, v118
	v_add_f32_e32 v50, v50, v203
	v_add_f32_e32 v50, v50, v204
	v_add_f32_e32 v50, v50, v205
	v_add_f32_e32 v50, v50, v206
	s_waitcnt lgkmcnt(4)
	v_mfma_f32_32x32x16_bf16 v[2:17], v[88:91], v[64:67], v[2:17]
	v_max3_f32 v51, v51, v119, v120
	v_max3_f32 v51, v51, v121, v121
	v_add_f32_e32 v50, v50, v207
	v_add_f32_e32 v50, v50, v208
	v_add_f32_e32 v50, v50, v209
	v_add_f32_e32 v50, v50, v210
	s_setprio 0
	ds_read_b128 v[146:149], v165 offset:9248
	ds_read_b128 v[60:63], v165 offset:13856
	v_add_f32_e32 v50, v1, v50
	v_mov_b32_e32 v1, v51
	s_nop 1
	v_permlane32_swap_b32_e32 v51, v1
	v_max_f32_e32 v1, v1, v1
	v_max_f32_e32 v51, v51, v51
	v_max_f32_e32 v1, v51, v1
	v_cmp_lt_f32_e32 vcc, s52, v1
	s_cbranch_vccz .LBB0_643
	v_max_f32_e32 v1, v1, v1
	v_max_f32_e32 v68, 0, v1
	v_add_f32_e32 v183, v183, v68
	v_xor_b32_e32 v34, 0x80000000, v183
	v_pk_add_f32 v[122:123], v[122:123], v[68:69] op_sel_hi:[1,0] neg_lo:[0,1] neg_hi:[0,1]
	v_pk_add_f32 v[106:107], v[106:107], v[68:69] op_sel_hi:[1,0] neg_lo:[0,1] neg_hi:[0,1]
	v_pk_add_f32 v[124:125], v[124:125], v[68:69] op_sel_hi:[1,0] neg_lo:[0,1] neg_hi:[0,1]
	v_pk_add_f32 v[108:109], v[108:109], v[68:69] op_sel_hi:[1,0] neg_lo:[0,1] neg_hi:[0,1]
	v_pk_add_f32 v[126:127], v[126:127], v[68:69] op_sel_hi:[1,0] neg_lo:[0,1] neg_hi:[0,1]
	v_pk_add_f32 v[110:111], v[110:111], v[68:69] op_sel_hi:[1,0] neg_lo:[0,1] neg_hi:[0,1]
	v_pk_add_f32 v[128:129], v[128:129], v[68:69] op_sel_hi:[1,0] neg_lo:[0,1] neg_hi:[0,1]
	v_pk_add_f32 v[112:113], v[112:113], v[68:69] op_sel_hi:[1,0] neg_lo:[0,1] neg_hi:[0,1]
	v_pk_add_f32 v[130:131], v[130:131], v[68:69] op_sel_hi:[1,0] neg_lo:[0,1] neg_hi:[0,1]
	v_pk_add_f32 v[114:115], v[114:115], v[68:69] op_sel_hi:[1,0] neg_lo:[0,1] neg_hi:[0,1]
	v_pk_add_f32 v[132:133], v[132:133], v[68:69] op_sel_hi:[1,0] neg_lo:[0,1] neg_hi:[0,1]
	v_pk_add_f32 v[116:117], v[116:117], v[68:69] op_sel_hi:[1,0] neg_lo:[0,1] neg_hi:[0,1]
	v_pk_add_f32 v[134:135], v[134:135], v[68:69] op_sel_hi:[1,0] neg_lo:[0,1] neg_hi:[0,1]
	v_pk_add_f32 v[118:119], v[118:119], v[68:69] op_sel_hi:[1,0] neg_lo:[0,1] neg_hi:[0,1]
	v_pk_add_f32 v[136:137], v[136:137], v[68:69] op_sel_hi:[1,0] neg_lo:[0,1] neg_hi:[0,1]
	v_pk_add_f32 v[120:121], v[120:121], v[68:69] op_sel_hi:[1,0] neg_lo:[0,1] neg_hi:[0,1]
	v_exp_f32_e64 v68, -v68
	v_mov_b32_e32 v35, v34
	v_mov_b32_e32 v36, v34
	v_mov_b32_e32 v37, v34
	v_mov_b32_e32 v38, v34
	v_mov_b32_e32 v39, v34
	v_mov_b32_e32 v40, v34
	v_mov_b32_e32 v41, v34
	v_mov_b32_e32 v42, v34
	v_mov_b32_e32 v43, v34
	v_mov_b32_e32 v44, v34
	v_mov_b32_e32 v45, v34
	v_mov_b32_e32 v46, v34
	v_mov_b32_e32 v47, v34
	v_mov_b32_e32 v48, v34
	v_mov_b32_e32 v49, v34
	s_nop 11
	v_pk_mul_f32 v[32:33], v[32:33], v[68:69] op_sel_hi:[1,0]
	v_pk_mul_f32 v[30:31], v[30:31], v[68:69] op_sel_hi:[1,0]
	v_pk_mul_f32 v[28:29], v[28:29], v[68:69] op_sel_hi:[1,0]
	v_pk_mul_f32 v[26:27], v[26:27], v[68:69] op_sel_hi:[1,0]
	v_pk_mul_f32 v[24:25], v[24:25], v[68:69] op_sel_hi:[1,0]
	v_pk_mul_f32 v[22:23], v[22:23], v[68:69] op_sel_hi:[1,0]
	v_pk_mul_f32 v[20:21], v[20:21], v[68:69] op_sel_hi:[1,0]
	v_pk_mul_f32 v[18:19], v[18:19], v[68:69] op_sel_hi:[1,0]
	v_pk_mul_f32 v[16:17], v[16:17], v[68:69] op_sel_hi:[1,0]
	v_pk_mul_f32 v[14:15], v[14:15], v[68:69] op_sel_hi:[1,0]
	v_pk_mul_f32 v[12:13], v[12:13], v[68:69] op_sel_hi:[1,0]
	v_pk_mul_f32 v[10:11], v[10:11], v[68:69] op_sel_hi:[1,0]
	v_pk_mul_f32 v[8:9], v[8:9], v[68:69] op_sel_hi:[1,0]
	v_pk_mul_f32 v[6:7], v[6:7], v[68:69] op_sel_hi:[1,0]
	v_pk_mul_f32 v[4:5], v[4:5], v[68:69] op_sel_hi:[1,0]
	v_pk_mul_f32 v[2:3], v[2:3], v[68:69] op_sel_hi:[1,0]
	v_mul_f32_e32 v50, v50, v68

.LBB0_661:
	s_add_i32 s26, s13, -7
	s_lshl_b32 s92, s26, 13
	s_add_u32 vcc_lo, s100, s92
	s_addc_u32 vcc_hi, s101, 0
	global_load_dwordx4 v[2:5], v248, vcc
	s_add_i32 s26, s13, -8
	s_lshl_b32 s92, s26, 7
	s_add_u32 vcc_lo, s98, s92
	s_addc_u32 vcc_hi, s99, 0
	global_load_dwordx4 v[6:9], v249, vcc
	s_mul_i32 s28, s27, 0x2400
	s_add_i32 s26, s13, -7
	s_add_i32 s29, s28, 0xffffdc00
	s_cmp_lg_u32 s27, 0
	s_cselect_b32 s29, s29, 0x9000
	v_add_u32_e32 v1, s29, v195
	ds_read_b128 v[10:13], v1 offset:36864
	ds_read_b128 v[66:69], v1 offset:36896
	ds_read_b128 v[70:73], v1 offset:41472
	ds_read_b128 v[74:77], v1 offset:41504
	ds_read_b128 v[128:131], v1 offset:36928
	ds_read_b128 v[132:135], v1 offset:36960
	ds_read_b128 v[148:151], v1 offset:41536
	ds_read_b128 v[160:163], v1 offset:41568
	s_setprio 3
	v_cvt_pk_bf16_f32 v210, v116, v117
	v_cvt_pk_bf16_f32 v211, v118, v119
	v_cvt_pk_bf16_f32 v212, v112, v113
	v_cvt_pk_bf16_f32 v213, v114, v115
	s_waitcnt lgkmcnt(7)
	s_nop 0
	v_mfma_f32_32x32x16_bf16 v[16:31], v[10:13], v[210:213], v[16:31]
	v_add_f32_e32 v1, v116, v117
	v_add_f32_e32 v1, v1, v118
	v_add_f32_e32 v1, v1, v119
	s_waitcnt lgkmcnt(5)
	v_mfma_f32_32x32x16_bf16 v[32:47], v[70:73], v[210:213], v[32:47]
	v_cvt_pk_bf16_f32 v10, v187, v186
	v_cvt_pk_bf16_f32 v11, v185, v184
	v_cvt_pk_bf16_f32 v12, v147, v146
	v_cvt_pk_bf16_f32 v13, v145, v144
	v_add_f32_e32 v1, v1, v112
	v_add_f32_e32 v1, v1, v113
	v_add_f32_e32 v1, v1, v114
	v_add_f32_e32 v1, v1, v115
	s_nop 0
	v_mfma_f32_32x32x16_bf16 v[16:31], v[66:69], v[10:13], v[16:31]
	v_add_f32_e32 v1, v1, v187
	v_add_f32_e32 v1, v1, v186
	v_add_f32_e32 v1, v1, v185
	v_add_f32_e32 v1, v1, v184
	s_waitcnt lgkmcnt(4)
	v_mfma_f32_32x32x16_bf16 v[32:47], v[74:77], v[10:13], v[32:47]
	v_cvt_pk_bf16_f32 v66, v143, v142
	v_cvt_pk_bf16_f32 v67, v141, v140
	v_cvt_pk_bf16_f32 v68, v139, v138
	v_cvt_pk_bf16_f32 v69, v137, v136
	v_add_f32_e32 v1, v1, v147
	v_add_f32_e32 v1, v1, v146
	v_add_f32_e32 v1, v1, v145
	v_add_f32_e32 v1, v1, v144
	s_waitcnt lgkmcnt(3)
	v_mfma_f32_32x32x16_bf16 v[16:31], v[128:131], v[66:69], v[16:31]
	v_add_f32_e32 v1, v1, v143
	v_add_f32_e32 v1, v1, v142
	v_add_f32_e32 v1, v1, v141
	v_add_f32_e32 v1, v1, v140
	s_waitcnt lgkmcnt(1)
	v_mfma_f32_32x32x16_bf16 v[32:47], v[148:151], v[66:69], v[32:47]
	v_cvt_pk_bf16_f32 v10, v123, v122
	v_cvt_pk_bf16_f32 v11, v121, v120
	v_cvt_pk_bf16_f32 v12, v127, v126
	v_cvt_pk_bf16_f32 v13, v125, v124
	v_add_f32_e32 v1, v1, v139
	v_add_f32_e32 v1, v1, v138
	v_add_f32_e32 v1, v1, v137
	v_add_f32_e32 v1, v1, v136
	s_nop 0
	v_mfma_f32_32x32x16_bf16 v[16:31], v[132:135], v[10:13], v[16:31]
	v_add_f32_e32 v1, v1, v123
	v_add_f32_e32 v1, v1, v122
	v_add_f32_e32 v1, v1, v121
	v_add_f32_e32 v1, v1, v120
	s_waitcnt lgkmcnt(0)
	v_mfma_f32_32x32x16_bf16 v[32:47], v[160:163], v[10:13], v[32:47]
	v_add_f32_e32 v1, v1, v127
	v_add_f32_e32 v1, v1, v126
	v_add_f32_e32 v1, v1, v125
	v_add_f32_e32 v1, v1, v124
	s_setprio 2
	s_waitcnt lgkmcnt(0)
	s_barrier
	ds_read_b128 v[240:243], v195 offset:18432
	ds_read_b128 v[244:247], v195 offset:23040
	ds_read_b128 v[66:69], v195 offset:18464
	ds_read_b128 v[74:77], v195 offset:23072
	ds_read_b128 v[144:147], v195 offset:18496
	ds_read_b128 v[148:151], v195 offset:18528
	ds_read_b128 v[160:163], v195 offset:23104
	ds_read_b128 v[184:187], v195 offset:23136
	v_exp_f32_e32 v166, v96
	v_exp_f32_e32 v167, v97
	v_exp_f32_e32 v210, v98
	v_exp_f32_e32 v211, v99
	s_waitcnt lgkmcnt(6)
	v_mfma_f32_32x32x16_bf16 v[128:143], v[240:243], v[180:183], v[48:63]
	s_waitcnt lgkmcnt(5)
	v_mfma_f32_32x32x16_bf16 v[112:127], v[244:247], v[180:183], v[48:63]
	v_exp_f32_e32 v212, v100
	v_exp_f32_e32 v213, v101
	v_exp_f32_e32 v214, v102
	v_exp_f32_e32 v215, v103
	v_mfma_f32_32x32x16_bf16 v[128:143], v[66:69], v[176:179], v[128:143]
	v_exp_f32_e32 v100, v104
	v_exp_f32_e32 v101, v105
	v_exp_f32_e32 v102, v106
	v_exp_f32_e32 v103, v107
	s_waitcnt lgkmcnt(4)
	v_mfma_f32_32x32x16_bf16 v[112:127], v[74:77], v[176:179], v[112:127]
	v_exp_f32_e32 v104, v108
	v_exp_f32_e32 v105, v109
	v_exp_f32_e32 v106, v110
	v_exp_f32_e32 v107, v111
	s_waitcnt lgkmcnt(3)
	v_mfma_f32_32x32x16_bf16 v[128:143], v[144:147], v[172:175], v[128:143]
	v_exp_f32_e32 v108, v80
	v_exp_f32_e32 v109, v81
	v_exp_f32_e32 v110, v82
	v_exp_f32_e32 v111, v83
	s_waitcnt lgkmcnt(1)
	v_mfma_f32_32x32x16_bf16 v[112:127], v[160:163], v[172:175], v[112:127]
	v_exp_f32_e32 v144, v84
	v_exp_f32_e32 v145, v85
	v_exp_f32_e32 v146, v86
	v_exp_f32_e32 v147, v87
	v_mfma_f32_32x32x16_bf16 v[128:143], v[148:151], v[168:171], v[128:143]
	v_exp_f32_e32 v216, v88
	v_exp_f32_e32 v217, v89
	v_exp_f32_e32 v218, v90
	v_exp_f32_e32 v219, v91
	s_waitcnt lgkmcnt(0)
	v_mfma_f32_32x32x16_bf16 v[112:127], v[184:187], v[168:171], v[112:127]
	v_exp_f32_e32 v148, v92
	v_exp_f32_e32 v149, v93
	v_exp_f32_e32 v150, v94
	v_exp_f32_e32 v151, v95
	v_add_f32_e32 v1, v64, v1
	v_add_u32_e32 v92, s28, v195
	ds_read_b128 v[64:67], v92 offset:41472
	ds_read_b128 v[68:71], v92 offset:36864
	ds_read_b128 v[72:75], v92 offset:36896
	ds_read_b128 v[76:79], v92 offset:41504
	ds_read_b128 v[80:83], v92 offset:36928
	ds_read_b128 v[84:87], v92 offset:41536
	ds_read_b128 v[88:91], v92 offset:36960
	ds_read_b128 v[92:95], v92 offset:41568
	ds_read_b128 v[240:243], v195 offset:27648
	ds_read_b128 v[244:247], v195 offset:32256
	s_cmp_gt_i32 s27, 2
	s_cselect_b32 s29, -3, 2
	s_add_i32 s29, s29, s27
	s_add_i32 s28, s13, -6
	s_mulk_i32 s29, 0x2400
	s_min_u32 s28, s28, s12
	v_add_u32_e32 v10, s29, v208
	s_min_u32 s26, s26, s12
	s_lshl_b32 s92, s28, 13
	s_waitcnt vmcnt(3)
	ds_write_b128 v208, v[152:155]
	s_waitcnt vmcnt(2)
	ds_write_b128 v10, v[156:159] offset:36864
	s_add_u32 vcc_lo, s100, s92
	s_addc_u32 vcc_hi, s101, 0
	global_load_dwordx4 v[10:13], v248, vcc
	s_lshl_b32 s92, s26, 7
	s_add_u32 vcc_lo, s98, s92
	s_addc_u32 vcc_hi, s99, 0
	global_load_dwordx4 v[160:163], v249, vcc
	s_add_i32 s29, s27, 1
	s_setprio 1
	v_cvt_pk_bf16_f32 v96, v166, v167
	v_cvt_pk_bf16_f32 v97, v210, v211
	v_cvt_pk_bf16_f32 v98, v212, v213
	v_cvt_pk_bf16_f32 v99, v214, v215
	s_waitcnt lgkmcnt(10)
	s_nop 0
	v_mfma_f32_32x32x16_bf16 v[16:31], v[68:71], v[96:99], v[16:31]
	v_add_f32_e32 v184, v166, v167
	v_add_f32_e32 v184, v184, v210
	v_add_f32_e32 v184, v184, v211
	s_nop 0
	v_mfma_f32_32x32x16_bf16 v[32:47], v[64:67], v[96:99], v[32:47]
	v_cvt_pk_bf16_f32 v68, v100, v101
	v_cvt_pk_bf16_f32 v69, v102, v103
	v_cvt_pk_bf16_f32 v70, v104, v105
	v_cvt_pk_bf16_f32 v71, v106, v107
	v_add_f32_e32 v184, v184, v212
	v_add_f32_e32 v184, v184, v213
	v_add_f32_e32 v184, v184, v214
	v_add_f32_e32 v184, v184, v215
	s_waitcnt lgkmcnt(9)
	v_mfma_f32_32x32x16_bf16 v[16:31], v[72:75], v[68:71], v[16:31]
	v_add_f32_e32 v184, v184, v100
	v_add_f32_e32 v184, v184, v101
	v_add_f32_e32 v184, v184, v102
	v_add_f32_e32 v184, v184, v103
	s_waitcnt lgkmcnt(8)
	v_mfma_f32_32x32x16_bf16 v[32:47], v[76:79], v[68:71], v[32:47]
	v_cvt_pk_bf16_f32 v64, v108, v109
	v_cvt_pk_bf16_f32 v65, v110, v111
	v_cvt_pk_bf16_f32 v66, v144, v145
	v_cvt_pk_bf16_f32 v67, v146, v147
	v_add_f32_e32 v184, v184, v104
	v_add_f32_e32 v184, v184, v105
	v_add_f32_e32 v184, v184, v106
	v_add_f32_e32 v184, v184, v107
	s_waitcnt lgkmcnt(7)
	v_mfma_f32_32x32x16_bf16 v[16:31], v[80:83], v[64:67], v[16:31]
	v_add_f32_e32 v184, v184, v108
	v_add_f32_e32 v184, v184, v109
	v_add_f32_e32 v184, v184, v110
	v_add_f32_e32 v184, v184, v111
	s_waitcnt lgkmcnt(6)
	v_mfma_f32_32x32x16_bf16 v[32:47], v[84:87], v[64:67], v[32:47]
	v_cvt_pk_bf16_f32 v68, v216, v217
	v_cvt_pk_bf16_f32 v69, v218, v219
	v_cvt_pk_bf16_f32 v70, v148, v149
	v_cvt_pk_bf16_f32 v71, v150, v151
	v_add_f32_e32 v184, v184, v144
	v_add_f32_e32 v184, v184, v145
	v_add_f32_e32 v184, v184, v146
	v_add_f32_e32 v184, v184, v147
	s_waitcnt lgkmcnt(5)
	v_mfma_f32_32x32x16_bf16 v[16:31], v[88:91], v[68:71], v[16:31]
	v_add_f32_e32 v184, v184, v216
	v_add_f32_e32 v184, v184, v217
	v_add_f32_e32 v184, v184, v218
	v_add_f32_e32 v184, v184, v219
	s_waitcnt lgkmcnt(4)
	v_mfma_f32_32x32x16_bf16 v[32:47], v[92:95], v[68:71], v[32:47]
	v_add_f32_e32 v184, v184, v148
	v_add_f32_e32 v184, v184, v149
	v_add_f32_e32 v184, v184, v150
	v_add_f32_e32 v184, v184, v151
	s_setprio 0
	ds_read_b128 v[68:71], v195 offset:27680
	ds_read_b128 v[76:79], v195 offset:32288
	ds_read_b128 v[80:83], v195 offset:27712
	ds_read_b128 v[84:87], v195 offset:27744
	ds_read_b128 v[88:91], v195 offset:32320
	ds_read_b128 v[92:95], v195 offset:32352
	s_cmp_lg_u32 s27, 4
	s_cselect_b32 s26, s29, 0
	s_waitcnt lgkmcnt(6)
	v_mfma_f32_32x32x16_bf16 v[144:159], v[240:243], v[180:183], v[48:63]
	v_exp_f32_e32 v166, v128
	v_exp_f32_e32 v167, v129
	v_exp_f32_e32 v185, v130
	v_exp_f32_e32 v186, v131
	s_waitcnt lgkmcnt(5)
	v_mfma_f32_32x32x16_bf16 v[96:111], v[244:247], v[180:183], v[48:63]
	v_exp_f32_e32 v128, v132
	v_exp_f32_e32 v129, v133
	v_exp_f32_e32 v130, v134
	v_exp_f32_e32 v131, v135
	v_mfma_f32_32x32x16_bf16 v[144:159], v[68:71], v[176:179], v[144:159]
	v_exp_f32_e32 v132, v136
	v_exp_f32_e32 v133, v137
	v_exp_f32_e32 v134, v138
	v_exp_f32_e32 v135, v139
	s_waitcnt lgkmcnt(4)
	v_mfma_f32_32x32x16_bf16 v[96:111], v[76:79], v[176:179], v[96:111]
	v_exp_f32_e32 v136, v140
	v_exp_f32_e32 v137, v141
	v_exp_f32_e32 v138, v142
	v_exp_f32_e32 v139, v143
	s_waitcnt lgkmcnt(3)
	v_mfma_f32_32x32x16_bf16 v[144:159], v[80:83], v[172:175], v[144:159]
	v_exp_f32_e32 v140, v112
	v_exp_f32_e32 v141, v113
	v_exp_f32_e32 v142, v114
	v_exp_f32_e32 v143, v115
	s_waitcnt lgkmcnt(1)
	v_mfma_f32_32x32x16_bf16 v[96:111], v[88:91], v[172:175], v[96:111]
	v_exp_f32_e32 v187, v116
	v_exp_f32_e32 v210, v117
	v_exp_f32_e32 v211, v118
	v_exp_f32_e32 v212, v119
	v_mfma_f32_32x32x16_bf16 v[144:159], v[84:87], v[168:171], v[144:159]
	v_exp_f32_e32 v116, v120
	v_exp_f32_e32 v117, v121
	v_exp_f32_e32 v118, v122
	v_exp_f32_e32 v119, v123
	s_waitcnt lgkmcnt(0)
	v_mfma_f32_32x32x16_bf16 v[96:111], v[92:95], v[168:171], v[96:111]
	v_exp_f32_e32 v120, v124
	v_exp_f32_e32 v121, v125
	v_exp_f32_e32 v122, v126
	v_exp_f32_e32 v123, v127
	s_cmp_gt_i32 s26, 2
	s_cselect_b32 s27, -3, 2
	s_add_i32 s27, s27, s26
	s_mulk_i32 s27, 0x2400
	s_waitcnt vmcnt(3)
	ds_write_b128 v208, v[2:5] offset:9216
	v_add_u32_e32 v2, s27, v208
	s_add_i32 s27, s26, 1
	s_cmp_lg_u32 s26, 4
	s_cselect_b32 s26, s27, 0
	s_add_i32 s27, s13, -5
	s_min_u32 s27, s27, s12
	s_lshl_b32 s92, s27, 13
	s_waitcnt vmcnt(2)
	ds_write_b128 v2, v[6:9] offset:36864
	s_add_u32 vcc_lo, s100, s92
	s_addc_u32 vcc_hi, s101, 0
	global_load_dwordx4 v[6:9], v248, vcc
	s_lshl_b32 s92, s28, 7
	s_add_u32 vcc_lo, s98, s92
	s_addc_u32 vcc_hi, s99, 0
	global_load_dwordx4 v[2:5], v249, vcc
	s_nop 0
	s_mul_i32 s28, s26, 0x2400
	s_add_i32 s29, s28, 0xffffdc00
	s_cmp_lg_u32 s26, 0
	s_cselect_b32 s29, s29, 0x9000
	v_add_u32_e32 v92, s29, v195
	ds_read_b128 v[64:67], v92 offset:36864
	ds_read_b128 v[68:71], v92 offset:36896
	ds_read_b128 v[72:75], v92 offset:41472
	ds_read_b128 v[76:79], v92 offset:41504
	ds_read_b128 v[80:83], v92 offset:36928
	ds_read_b128 v[84:87], v92 offset:36960
	ds_read_b128 v[88:91], v92 offset:41536
	ds_read_b128 v[92:95], v92 offset:41568
	s_setprio 3
	v_cvt_pk_bf16_f32 v112, v166, v167
	v_cvt_pk_bf16_f32 v113, v185, v186
	v_cvt_pk_bf16_f32 v114, v128, v129
	v_cvt_pk_bf16_f32 v115, v130, v131
	s_waitcnt lgkmcnt(7)
	s_nop 0
	v_mfma_f32_32x32x16_bf16 v[16:31], v[64:67], v[112:115], v[16:31]
	v_add_f32_e32 v213, v166, v167
	v_add_f32_e32 v213, v213, v185
	v_add_f32_e32 v213, v213, v186
	s_waitcnt lgkmcnt(5)
	v_mfma_f32_32x32x16_bf16 v[32:47], v[72:75], v[112:115], v[32:47]
	v_cvt_pk_bf16_f32 v64, v132, v133
	v_cvt_pk_bf16_f32 v65, v134, v135
	v_cvt_pk_bf16_f32 v66, v136, v137
	v_cvt_pk_bf16_f32 v67, v138, v139
	v_add_f32_e32 v213, v213, v128
	v_add_f32_e32 v213, v213, v129
	v_add_f32_e32 v213, v213, v130
	v_add_f32_e32 v213, v213, v131
	s_nop 0
	v_mfma_f32_32x32x16_bf16 v[16:31], v[68:71], v[64:67], v[16:31]
	v_add_f32_e32 v213, v213, v132
	v_add_f32_e32 v213, v213, v133
	v_add_f32_e32 v213, v213, v134
	v_add_f32_e32 v213, v213, v135
	s_waitcnt lgkmcnt(4)
	v_mfma_f32_32x32x16_bf16 v[32:47], v[76:79], v[64:67], v[32:47]
	v_cvt_pk_bf16_f32 v68, v140, v141
	v_cvt_pk_bf16_f32 v69, v142, v143
	v_cvt_pk_bf16_f32 v70, v187, v210
	v_cvt_pk_bf16_f32 v71, v211, v212
	v_add_f32_e32 v213, v213, v136
	v_add_f32_e32 v213, v213, v137
	v_add_f32_e32 v213, v213, v138
	v_add_f32_e32 v213, v213, v139
	s_waitcnt lgkmcnt(3)
	v_mfma_f32_32x32x16_bf16 v[16:31], v[80:83], v[68:71], v[16:31]
	v_add_f32_e32 v213, v213, v140
	v_add_f32_e32 v213, v213, v141
	v_add_f32_e32 v213, v213, v142
	v_add_f32_e32 v213, v213, v143
	s_waitcnt lgkmcnt(1)
	v_mfma_f32_32x32x16_bf16 v[32:47], v[88:91], v[68:71], v[32:47]
	v_cvt_pk_bf16_f32 v64, v116, v117
	v_cvt_pk_bf16_f32 v65, v118, v119
	v_cvt_pk_bf16_f32 v66, v120, v121
	v_cvt_pk_bf16_f32 v67, v122, v123
	v_add_f32_e32 v213, v213, v187
	v_add_f32_e32 v213, v213, v210
	v_add_f32_e32 v213, v213, v211
	v_add_f32_e32 v213, v213, v212
	s_nop 0
	v_mfma_f32_32x32x16_bf16 v[16:31], v[84:87], v[64:67], v[16:31]
	v_add_f32_e32 v213, v213, v116
	v_add_f32_e32 v213, v213, v117
	v_add_f32_e32 v213, v213, v118
	v_add_f32_e32 v213, v213, v119
	s_waitcnt lgkmcnt(0)
	v_mfma_f32_32x32x16_bf16 v[32:47], v[92:95], v[64:67], v[32:47]
	v_add_f32_e32 v213, v213, v120
	v_add_f32_e32 v213, v213, v121
	v_add_f32_e32 v213, v213, v122
	v_add_f32_e32 v213, v213, v123
	s_setprio 2
	s_waitcnt lgkmcnt(0)
	s_barrier
	ds_read_b128 v[240:243], v195
	ds_read_b128 v[244:247], v195 offset:4608
	ds_read_b128 v[116:119], v195 offset:32
	ds_read_b128 v[120:123], v195 offset:4640
	ds_read_b128 v[124:127], v195 offset:64
	ds_read_b128 v[128:131], v195 offset:4672
	ds_read_b128 v[132:135], v195 offset:96
	ds_read_b128 v[136:139], v195 offset:4704
	v_add_f32_e32 v1, v1, v184
	v_exp_f32_e32 v140, v144
	v_exp_f32_e32 v141, v145
	v_exp_f32_e32 v142, v146
	v_exp_f32_e32 v143, v147
	s_waitcnt lgkmcnt(6)
	v_mfma_f32_32x32x16_bf16 v[80:95], v[240:243], v[180:183], v[48:63]
	v_mfma_f32_32x32x16_bf16 v[64:79], v[244:247], v[180:183], v[48:63]
	v_exp_f32_e32 v144, v148
	v_exp_f32_e32 v145, v149
	v_exp_f32_e32 v146, v150
	v_exp_f32_e32 v147, v151
	s_waitcnt lgkmcnt(5)
	v_mfma_f32_32x32x16_bf16 v[80:95], v[116:119], v[176:179], v[80:95]
	v_exp_f32_e32 v148, v152
	v_exp_f32_e32 v149, v153
	v_exp_f32_e32 v150, v154
	v_exp_f32_e32 v151, v155
	s_waitcnt lgkmcnt(4)
	v_mfma_f32_32x32x16_bf16 v[64:79], v[120:123], v[176:179], v[64:79]
	v_exp_f32_e32 v152, v156
	v_exp_f32_e32 v153, v157
	v_exp_f32_e32 v154, v158
	v_exp_f32_e32 v155, v159
	s_waitcnt lgkmcnt(3)
	v_mfma_f32_32x32x16_bf16 v[80:95], v[124:127], v[172:175], v[80:95]
	v_exp_f32_e32 v156, v96
	v_exp_f32_e32 v157, v97
	v_exp_f32_e32 v158, v98
	v_exp_f32_e32 v159, v99
	s_waitcnt lgkmcnt(2)
	v_mfma_f32_32x32x16_bf16 v[64:79], v[128:131], v[172:175], v[64:79]
	v_exp_f32_e32 v166, v100
	v_exp_f32_e32 v167, v101
	v_exp_f32_e32 v184, v102
	v_exp_f32_e32 v185, v103
	s_waitcnt lgkmcnt(1)
	v_mfma_f32_32x32x16_bf16 v[80:95], v[132:135], v[168:171], v[80:95]
	v_exp_f32_e32 v186, v104
	v_exp_f32_e32 v187, v105
	v_exp_f32_e32 v210, v106
	v_exp_f32_e32 v211, v107
	s_waitcnt lgkmcnt(0)
	v_mfma_f32_32x32x16_bf16 v[64:79], v[136:139], v[168:171], v[64:79]
	v_exp_f32_e32 v212, v108
	v_exp_f32_e32 v214, v109
	v_exp_f32_e32 v215, v110
	v_exp_f32_e32 v216, v111
	v_add_u32_e32 v124, s28, v195
	ds_read_b128 v[96:99], v124 offset:41472
	ds_read_b128 v[100:103], v124 offset:36864
	ds_read_b128 v[104:107], v124 offset:36896
	ds_read_b128 v[108:111], v124 offset:41504
	ds_read_b128 v[112:115], v124 offset:36928
	ds_read_b128 v[116:119], v124 offset:41536
	ds_read_b128 v[120:123], v124 offset:36960
	ds_read_b128 v[124:127], v124 offset:41568
	ds_read_b128 v[240:243], v195 offset:9216
	ds_read_b128 v[244:247], v195 offset:13824
	s_cmp_gt_i32 s26, 2
	s_cselect_b32 s29, -3, 2
	s_add_i32 s29, s29, s26
	s_mulk_i32 s29, 0x2400
	s_waitcnt vmcnt(3)
	ds_write_b128 v208, v[10:13] offset:18432
	v_add_u32_e32 v10, s29, v208
	s_mov_b32 s29, 0x1da90000
	s_waitcnt vmcnt(2)
	ds_write_b128 v10, v[160:163] offset:36864
	s_add_i32 s92, s13, -4
	s_lshl_b32 s92, s92, 13
	s_add_u32 vcc_lo, s100, s92
	s_addc_u32 vcc_hi, s101, 0
	global_load_dwordx4 v[128:131], v248, vcc
	s_lshl_b32 s92, s27, 7
	s_add_u32 vcc_lo, s98, s92
	s_addc_u32 vcc_hi, s99, 0
	global_load_dwordx4 v[10:13], v249, vcc
	v_add_f32_e32 v1, v1, v213
	s_add_i32 s28, s26, 1
	s_setprio 1
	v_cvt_pk_bf16_f32 v132, v140, v141
	v_cvt_pk_bf16_f32 v133, v142, v143
	v_cvt_pk_bf16_f32 v134, v144, v145
	v_cvt_pk_bf16_f32 v135, v146, v147
	s_waitcnt lgkmcnt(10)
	s_nop 0
	v_mfma_f32_32x32x16_bf16 v[16:31], v[100:103], v[132:135], v[16:31]
	v_add_f32_e32 v160, v140, v141
	v_add_f32_e32 v160, v160, v142
	v_add_f32_e32 v160, v160, v143
	s_nop 0
	v_mfma_f32_32x32x16_bf16 v[32:47], v[96:99], v[132:135], v[32:47]
	v_cvt_pk_bf16_f32 v100, v148, v149
	v_cvt_pk_bf16_f32 v101, v150, v151
	v_cvt_pk_bf16_f32 v102, v152, v153
	v_cvt_pk_bf16_f32 v103, v154, v155
	v_add_f32_e32 v160, v160, v144
	v_add_f32_e32 v160, v160, v145
	v_add_f32_e32 v160, v160, v146
	v_add_f32_e32 v160, v160, v147
	s_waitcnt lgkmcnt(9)
	v_mfma_f32_32x32x16_bf16 v[16:31], v[104:107], v[100:103], v[16:31]
	v_add_f32_e32 v160, v160, v148
	v_add_f32_e32 v160, v160, v149
	v_add_f32_e32 v160, v160, v150
	v_add_f32_e32 v160, v160, v151
	s_waitcnt lgkmcnt(8)
	v_mfma_f32_32x32x16_bf16 v[32:47], v[108:111], v[100:103], v[32:47]
	v_cvt_pk_bf16_f32 v96, v156, v157
	v_cvt_pk_bf16_f32 v97, v158, v159
	v_cvt_pk_bf16_f32 v98, v166, v167
	v_cvt_pk_bf16_f32 v99, v184, v185
	v_add_f32_e32 v160, v160, v152
	v_add_f32_e32 v160, v160, v153
	v_add_f32_e32 v160, v160, v154
	v_add_f32_e32 v160, v160, v155
	s_waitcnt lgkmcnt(7)
	v_mfma_f32_32x32x16_bf16 v[16:31], v[112:115], v[96:99], v[16:31]
	v_add_f32_e32 v160, v160, v156
	v_add_f32_e32 v160, v160, v157
	v_add_f32_e32 v160, v160, v158
	v_add_f32_e32 v160, v160, v159
	s_waitcnt lgkmcnt(6)
	v_mfma_f32_32x32x16_bf16 v[32:47], v[116:119], v[96:99], v[32:47]
	v_cvt_pk_bf16_f32 v100, v186, v187
	v_cvt_pk_bf16_f32 v101, v210, v211
	v_cvt_pk_bf16_f32 v102, v212, v214
	v_cvt_pk_bf16_f32 v103, v215, v216
	v_add_f32_e32 v160, v160, v166
	v_add_f32_e32 v160, v160, v167
	v_add_f32_e32 v160, v160, v184
	v_add_f32_e32 v160, v160, v185
	s_waitcnt lgkmcnt(5)
	v_mfma_f32_32x32x16_bf16 v[16:31], v[120:123], v[100:103], v[16:31]
	v_add_f32_e32 v160, v160, v186
	v_add_f32_e32 v160, v160, v187
	v_add_f32_e32 v160, v160, v210
	v_add_f32_e32 v160, v160, v211
	s_waitcnt lgkmcnt(4)
	v_mfma_f32_32x32x16_bf16 v[32:47], v[124:127], v[100:103], v[32:47]
	v_add_f32_e32 v160, v160, v212
	v_add_f32_e32 v160, v160, v214
	v_add_f32_e32 v160, v160, v215
	v_add_f32_e32 v160, v160, v216
	s_setprio 0
	ds_read_b128 v[132:135], v195 offset:9248
	ds_read_b128 v[140:143], v195 offset:13856
	ds_read_b128 v[144:147], v195 offset:9280
	ds_read_b128 v[148:151], v195 offset:9312
	ds_read_b128 v[152:155], v195 offset:13888
	ds_read_b128 v[156:159], v195 offset:13920
	s_cmp_lg_u32 s26, 4
	s_cselect_b32 s26, s28, 0
	s_waitcnt lgkmcnt(6)
	v_mfma_f32_32x32x16_bf16 v[112:127], v[240:243], v[180:183], v[48:63]
	v_exp_f32_e32 v161, v80
	v_exp_f32_e32 v162, v81
	v_exp_f32_e32 v163, v82
	v_exp_f32_e32 v164, v83
	s_waitcnt lgkmcnt(5)
	v_mfma_f32_32x32x16_bf16 v[96:111], v[244:247], v[180:183], v[48:63]
	v_exp_f32_e32 v165, v84
	v_exp_f32_e32 v166, v85
	v_exp_f32_e32 v167, v86
	v_exp_f32_e32 v184, v87
	v_mfma_f32_32x32x16_bf16 v[112:127], v[132:135], v[176:179], v[112:127]
	v_exp_f32_e32 v136, v88
	v_exp_f32_e32 v137, v89
	v_exp_f32_e32 v138, v90
	v_exp_f32_e32 v139, v91
	s_waitcnt lgkmcnt(4)
	v_mfma_f32_32x32x16_bf16 v[96:111], v[140:143], v[176:179], v[96:111]
	v_exp_f32_e32 v185, v92
	v_exp_f32_e32 v186, v93
	v_exp_f32_e32 v187, v94
	v_exp_f32_e32 v210, v95
	s_waitcnt lgkmcnt(3)
	v_mfma_f32_32x32x16_bf16 v[112:127], v[144:147], v[172:175], v[112:127]
	v_exp_f32_e32 v140, v64
	v_exp_f32_e32 v141, v65
	v_exp_f32_e32 v142, v66
	v_exp_f32_e32 v143, v67
	s_waitcnt lgkmcnt(1)
	v_mfma_f32_32x32x16_bf16 v[96:111], v[152:155], v[172:175], v[96:111]
	v_exp_f32_e32 v144, v68
	v_exp_f32_e32 v145, v69
	v_exp_f32_e32 v146, v70
	v_exp_f32_e32 v147, v71
	v_mfma_f32_32x32x16_bf16 v[112:127], v[148:151], v[168:171], v[112:127]
	v_exp_f32_e32 v152, v72
	v_exp_f32_e32 v153, v73
	v_exp_f32_e32 v154, v74
	v_exp_f32_e32 v155, v75
	s_waitcnt lgkmcnt(0)
	v_mfma_f32_32x32x16_bf16 v[96:111], v[156:159], v[168:171], v[96:111]
	v_exp_f32_e32 v148, v76
	v_exp_f32_e32 v149, v77
	v_exp_f32_e32 v150, v78
	v_exp_f32_e32 v151, v79
	s_cmp_gt_i32 s26, 2
	s_cselect_b32 s27, -3, 2
	s_add_i32 s27, s27, s26
	s_mulk_i32 s27, 0x2400
	s_waitcnt vmcnt(3)
	ds_write_b128 v208, v[6:9] offset:27648
	v_add_u32_e32 v6, s27, v208
	s_add_i32 s27, s26, 1
	s_cmp_lg_u32 s26, 4
	s_cselect_b32 s27, s27, 0
	s_add_i32 s26, s13, -3
	s_min_u32 s28, s26, s12
	s_lshl_b32 s92, s28, 13
	s_waitcnt vmcnt(2)
	ds_write_b128 v6, v[2:5] offset:36864
	s_add_u32 vcc_lo, s100, s92
	s_addc_u32 vcc_hi, s101, 0
	global_load_dwordx4 v[6:9], v248, vcc
	s_nop 0
	s_add_i32 s92, s13, -4
	s_lshl_b32 s92, s92, 7
	s_add_u32 vcc_lo, s98, s92
	s_addc_u32 vcc_hi, s99, 0
	global_load_dwordx4 v[2:5], v249, vcc
	s_mul_i32 s29, s27, 0x2400
	s_add_i32 s34, s29, 0xffffdc00
	s_cmp_lg_u32 s27, 0
	s_cselect_b32 s34, s34, 0x9000
	v_add_u32_e32 v14, s34, v195
	ds_read_b128 v[64:67], v14 offset:36864
	ds_read_b128 v[68:71], v14 offset:36896
	ds_read_b128 v[72:75], v14 offset:41472
	ds_read_b128 v[76:79], v14 offset:41504
	ds_read_b128 v[80:83], v14 offset:36928
	ds_read_b128 v[84:87], v14 offset:36960
	ds_read_b128 v[88:91], v14 offset:41536
	ds_read_b128 v[92:95], v14 offset:41568
	s_setprio 3
	v_cvt_pk_bf16_f32 v132, v161, v162
	v_cvt_pk_bf16_f32 v133, v163, v164
	v_cvt_pk_bf16_f32 v134, v165, v166
	v_cvt_pk_bf16_f32 v135, v167, v184
	s_waitcnt lgkmcnt(7)
	s_nop 0
	v_mfma_f32_32x32x16_bf16 v[16:31], v[64:67], v[132:135], v[16:31]
	v_add_f32_e32 v14, v161, v162
	v_add_f32_e32 v14, v14, v163
	v_add_f32_e32 v14, v14, v164
	s_waitcnt lgkmcnt(5)
	v_mfma_f32_32x32x16_bf16 v[32:47], v[72:75], v[132:135], v[32:47]
	v_cvt_pk_bf16_f32 v64, v136, v137
	v_cvt_pk_bf16_f32 v65, v138, v139
	v_cvt_pk_bf16_f32 v66, v185, v186
	v_cvt_pk_bf16_f32 v67, v187, v210
	v_add_f32_e32 v14, v14, v165
	v_add_f32_e32 v14, v14, v166
	v_add_f32_e32 v14, v14, v167
	v_add_f32_e32 v14, v14, v184
	s_nop 0
	v_mfma_f32_32x32x16_bf16 v[16:31], v[68:71], v[64:67], v[16:31]
	v_add_f32_e32 v14, v14, v136
	v_add_f32_e32 v14, v14, v137
	v_add_f32_e32 v14, v14, v138
	v_add_f32_e32 v14, v14, v139
	s_waitcnt lgkmcnt(4)
	v_mfma_f32_32x32x16_bf16 v[32:47], v[76:79], v[64:67], v[32:47]
	v_cvt_pk_bf16_f32 v68, v140, v141
	v_cvt_pk_bf16_f32 v69, v142, v143
	v_cvt_pk_bf16_f32 v70, v144, v145
	v_cvt_pk_bf16_f32 v71, v146, v147
	v_add_f32_e32 v14, v14, v185
	v_add_f32_e32 v14, v14, v186
	v_add_f32_e32 v14, v14, v187
	v_add_f32_e32 v14, v14, v210
	s_waitcnt lgkmcnt(3)
	v_mfma_f32_32x32x16_bf16 v[16:31], v[80:83], v[68:71], v[16:31]
	v_add_f32_e32 v14, v14, v140
	v_add_f32_e32 v14, v14, v141
	v_add_f32_e32 v14, v14, v142
	v_add_f32_e32 v14, v14, v143
	s_waitcnt lgkmcnt(1)
	v_mfma_f32_32x32x16_bf16 v[32:47], v[88:91], v[68:71], v[32:47]
	v_cvt_pk_bf16_f32 v64, v152, v153
	v_cvt_pk_bf16_f32 v65, v154, v155
	v_cvt_pk_bf16_f32 v66, v148, v149
	v_cvt_pk_bf16_f32 v67, v150, v151
	v_add_f32_e32 v14, v14, v144
	v_add_f32_e32 v14, v14, v145
	v_add_f32_e32 v14, v14, v146
	v_add_f32_e32 v14, v14, v147
	s_nop 0
	v_mfma_f32_32x32x16_bf16 v[16:31], v[84:87], v[64:67], v[16:31]
	v_add_f32_e32 v14, v14, v152
	v_add_f32_e32 v14, v14, v153
	v_add_f32_e32 v14, v14, v154
	v_add_f32_e32 v14, v14, v155
	s_waitcnt lgkmcnt(0)
	v_mfma_f32_32x32x16_bf16 v[32:47], v[92:95], v[64:67], v[32:47]
	v_add_f32_e32 v14, v14, v148
	v_add_f32_e32 v14, v14, v149
	v_add_f32_e32 v14, v14, v150
	v_add_f32_e32 v14, v14, v151
	s_setprio 2
	s_waitcnt lgkmcnt(0)
	s_barrier
	ds_read_b128 v[240:243], v195 offset:18432
	ds_read_b128 v[244:247], v195 offset:23040
	ds_read_b128 v[136:139], v195 offset:18464
	ds_read_b128 v[140:143], v195 offset:23072
	ds_read_b128 v[144:147], v195 offset:18496
	ds_read_b128 v[148:151], v195 offset:23104
	ds_read_b128 v[152:155], v195 offset:18528
	ds_read_b128 v[156:159], v195 offset:23136
	v_add_f32_e32 v1, v1, v160
	v_exp_f32_e32 v160, v112
	v_exp_f32_e32 v161, v113
	v_exp_f32_e32 v162, v114
	v_exp_f32_e32 v163, v115
	s_waitcnt lgkmcnt(6)
	v_mfma_f32_32x32x16_bf16 v[80:95], v[240:243], v[180:183], v[48:63]
	v_mfma_f32_32x32x16_bf16 v[64:79], v[244:247], v[180:183], v[48:63]
	v_exp_f32_e32 v164, v116
	v_exp_f32_e32 v165, v117
	v_exp_f32_e32 v166, v118
	v_exp_f32_e32 v167, v119
	s_waitcnt lgkmcnt(5)
	v_mfma_f32_32x32x16_bf16 v[80:95], v[136:139], v[176:179], v[80:95]
	v_exp_f32_e32 v184, v120
	v_exp_f32_e32 v185, v121
	v_exp_f32_e32 v186, v122
	v_exp_f32_e32 v187, v123
	s_waitcnt lgkmcnt(4)
	v_mfma_f32_32x32x16_bf16 v[64:79], v[140:143], v[176:179], v[64:79]
	v_exp_f32_e32 v136, v124
	v_exp_f32_e32 v137, v125
	v_exp_f32_e32 v138, v126
	v_exp_f32_e32 v139, v127
	s_waitcnt lgkmcnt(3)
	v_mfma_f32_32x32x16_bf16 v[80:95], v[144:147], v[172:175], v[80:95]
	v_exp_f32_e32 v140, v96
	v_exp_f32_e32 v141, v97
	v_exp_f32_e32 v142, v98
	v_exp_f32_e32 v143, v99
	s_waitcnt lgkmcnt(2)
	v_mfma_f32_32x32x16_bf16 v[64:79], v[148:151], v[172:175], v[64:79]
	v_exp_f32_e32 v144, v100
	v_exp_f32_e32 v145, v101
	v_exp_f32_e32 v146, v102
	v_exp_f32_e32 v147, v103
	s_waitcnt lgkmcnt(1)
	v_mfma_f32_32x32x16_bf16 v[80:95], v[152:155], v[168:171], v[80:95]
	v_exp_f32_e32 v148, v104
	v_exp_f32_e32 v149, v105
	v_exp_f32_e32 v150, v106
	v_exp_f32_e32 v151, v107
	s_waitcnt lgkmcnt(0)
	v_mfma_f32_32x32x16_bf16 v[64:79], v[156:159], v[168:171], v[64:79]
	v_exp_f32_e32 v152, v108
	v_exp_f32_e32 v153, v109
	v_exp_f32_e32 v154, v110
	v_exp_f32_e32 v155, v111
	s_cmp_gt_i32 s27, 2
	s_cselect_b32 s34, -3, 2
	s_waitcnt vmcnt(3)
	ds_write_b128 v208, v[128:131]
	v_add_u32_e32 v128, s29, v195
	ds_read_b128 v[96:99], v128 offset:41472
	ds_read_b128 v[100:103], v128 offset:36864
	ds_read_b128 v[104:107], v128 offset:36896
	ds_read_b128 v[108:111], v128 offset:41504
	ds_read_b128 v[116:119], v128 offset:36928
	ds_read_b128 v[120:123], v128 offset:41536
	ds_read_b128 v[124:127], v128 offset:36960
	ds_read_b128 v[128:131], v128 offset:41568
	ds_read_b128 v[240:243], v195 offset:27648
	ds_read_b128 v[244:247], v195 offset:32256
	s_add_i32 s34, s34, s27
	s_add_i32 s29, s13, -2
	s_mulk_i32 s34, 0x2400
	s_min_u32 s29, s29, s12
	v_add_u32_e32 v15, s34, v208
	s_lshl_b32 s92, s29, 13
	s_waitcnt vmcnt(2)
	ds_write_b128 v15, v[10:13] offset:36864
	s_add_u32 vcc_lo, s100, s92
	s_addc_u32 vcc_hi, s101, 0
	global_load_dwordx4 v[10:13], v248, vcc
	s_lshl_b32 s92, s28, 7
	v_add_f32_e32 v1, v1, v14
	s_add_u32 vcc_lo, s98, s92
	s_addc_u32 vcc_hi, s99, 0
	global_load_dwordx4 v[112:115], v249, vcc
	s_add_i32 s34, s27, 1
	s_setprio 1
	v_cvt_pk_bf16_f32 v132, v160, v161
	v_cvt_pk_bf16_f32 v133, v162, v163
	v_cvt_pk_bf16_f32 v134, v164, v165
	v_cvt_pk_bf16_f32 v135, v166, v167
	s_waitcnt lgkmcnt(9)
	s_nop 0
	v_mfma_f32_32x32x16_bf16 v[16:31], v[100:103], v[132:135], v[16:31]
	v_add_f32_e32 v14, v160, v161
	v_add_f32_e32 v14, v14, v162
	v_add_f32_e32 v14, v14, v163
	s_nop 0
	v_mfma_f32_32x32x16_bf16 v[32:47], v[96:99], v[132:135], v[32:47]
	v_cvt_pk_bf16_f32 v100, v184, v185
	v_cvt_pk_bf16_f32 v101, v186, v187
	v_cvt_pk_bf16_f32 v102, v136, v137
	v_cvt_pk_bf16_f32 v103, v138, v139
	v_add_f32_e32 v14, v14, v164
	v_add_f32_e32 v14, v14, v165
	v_add_f32_e32 v14, v14, v166
	v_add_f32_e32 v14, v14, v167
	s_waitcnt lgkmcnt(8)
	v_mfma_f32_32x32x16_bf16 v[16:31], v[104:107], v[100:103], v[16:31]
	v_add_f32_e32 v14, v14, v184
	v_add_f32_e32 v14, v14, v185
	v_add_f32_e32 v14, v14, v186
	v_add_f32_e32 v14, v14, v187
	s_waitcnt lgkmcnt(7)
	v_mfma_f32_32x32x16_bf16 v[32:47], v[108:111], v[100:103], v[32:47]
	v_cvt_pk_bf16_f32 v96, v140, v141
	v_cvt_pk_bf16_f32 v97, v142, v143
	v_cvt_pk_bf16_f32 v98, v144, v145
	v_cvt_pk_bf16_f32 v99, v146, v147
	v_add_f32_e32 v14, v14, v136
	v_add_f32_e32 v14, v14, v137
	v_add_f32_e32 v14, v14, v138
	v_add_f32_e32 v14, v14, v139
	s_waitcnt lgkmcnt(6)
	v_mfma_f32_32x32x16_bf16 v[16:31], v[116:119], v[96:99], v[16:31]
	v_add_f32_e32 v14, v14, v140
	v_add_f32_e32 v14, v14, v141
	v_add_f32_e32 v14, v14, v142
	v_add_f32_e32 v14, v14, v143
	s_waitcnt lgkmcnt(5)
	v_mfma_f32_32x32x16_bf16 v[32:47], v[120:123], v[96:99], v[32:47]
	v_cvt_pk_bf16_f32 v100, v148, v149
	v_cvt_pk_bf16_f32 v101, v150, v151
	v_cvt_pk_bf16_f32 v102, v152, v153
	v_cvt_pk_bf16_f32 v103, v154, v155
	v_add_f32_e32 v14, v14, v144
	v_add_f32_e32 v14, v14, v145
	v_add_f32_e32 v14, v14, v146
	v_add_f32_e32 v14, v14, v147
	s_waitcnt lgkmcnt(4)
	v_mfma_f32_32x32x16_bf16 v[16:31], v[124:127], v[100:103], v[16:31]
	v_add_f32_e32 v14, v14, v148
	v_add_f32_e32 v14, v14, v149
	v_add_f32_e32 v14, v14, v150
	v_add_f32_e32 v14, v14, v151
	s_waitcnt lgkmcnt(3)
	v_mfma_f32_32x32x16_bf16 v[32:47], v[128:131], v[100:103], v[32:47]
	v_add_f32_e32 v14, v14, v152
	v_add_f32_e32 v14, v14, v153
	v_add_f32_e32 v14, v14, v154
	v_add_f32_e32 v14, v14, v155
	s_setprio 0
	ds_read_b128 v[116:119], v195 offset:27680
	ds_read_b128 v[124:127], v195 offset:32288
	ds_read_b128 v[128:131], v195 offset:27712
	ds_read_b128 v[132:135], v195 offset:27744
	ds_read_b128 v[136:139], v195 offset:32320
	ds_read_b128 v[140:143], v195 offset:32352
	s_cmp_lg_u32 s27, 4
	s_cselect_b32 s27, s34, 0
	s_waitcnt lgkmcnt(6)
	v_mfma_f32_32x32x16_bf16 v[152:167], v[240:243], v[180:183], v[48:63]
	v_exp_f32_e32 v15, v80
	v_exp_f32_e32 v144, v81
	v_exp_f32_e32 v145, v82
	v_exp_f32_e32 v146, v83
	s_waitcnt lgkmcnt(5)
	v_mfma_f32_32x32x16_bf16 v[96:111], v[244:247], v[180:183], v[48:63]
	v_exp_f32_e32 v147, v84
	v_exp_f32_e32 v148, v85
	v_exp_f32_e32 v149, v86
	v_exp_f32_e32 v150, v87
	v_mfma_f32_32x32x16_bf16 v[152:167], v[116:119], v[176:179], v[152:167]
	v_exp_f32_e32 v120, v88
	v_exp_f32_e32 v121, v89
	v_exp_f32_e32 v122, v90
	v_exp_f32_e32 v123, v91
	s_waitcnt lgkmcnt(4)
	v_mfma_f32_32x32x16_bf16 v[96:111], v[124:127], v[176:179], v[96:111]
	v_exp_f32_e32 v151, v92
	v_exp_f32_e32 v184, v93
	v_exp_f32_e32 v185, v94
	v_exp_f32_e32 v186, v95
	s_waitcnt lgkmcnt(3)
	v_mfma_f32_32x32x16_bf16 v[152:167], v[128:131], v[172:175], v[152:167]
	v_exp_f32_e32 v124, v64
	v_exp_f32_e32 v125, v65
	v_exp_f32_e32 v126, v66
	v_exp_f32_e32 v127, v67
	s_waitcnt lgkmcnt(1)
	v_mfma_f32_32x32x16_bf16 v[96:111], v[136:139], v[172:175], v[96:111]
	v_exp_f32_e32 v128, v68
	v_exp_f32_e32 v129, v69
	v_exp_f32_e32 v130, v70
	v_exp_f32_e32 v131, v71
	v_mfma_f32_32x32x16_bf16 v[152:167], v[132:135], v[168:171], v[152:167]
	v_exp_f32_e32 v136, v72
	v_exp_f32_e32 v137, v73
	v_exp_f32_e32 v138, v74
	v_exp_f32_e32 v139, v75
	s_waitcnt lgkmcnt(0)
	v_mfma_f32_32x32x16_bf16 v[96:111], v[140:143], v[168:171], v[96:111]
	v_exp_f32_e32 v132, v76
	v_exp_f32_e32 v133, v77
	v_exp_f32_e32 v134, v78
	v_exp_f32_e32 v135, v79
	s_cmp_gt_i32 s27, 2
	s_cselect_b32 s28, -3, 2
	s_add_i32 s28, s28, s27
	s_mulk_i32 s28, 0x2400
	s_waitcnt vmcnt(3)
	ds_write_b128 v208, v[6:9] offset:9216
	v_add_u32_e32 v6, s28, v208
	s_add_i32 s28, s27, 1
	s_cmp_lg_u32 s27, 4
	s_cselect_b32 s27, s28, 0
	s_add_i32 s28, s13, -1
	s_min_u32 s28, s28, s12
	s_lshl_b32 s92, s28, 13
	s_waitcnt vmcnt(2)
	ds_write_b128 v6, v[2:5] offset:36864
	s_add_u32 vcc_lo, s100, s92
	s_addc_u32 vcc_hi, s101, 0
	global_load_dwordx4 v[6:9], v248, vcc
	s_lshl_b32 s92, s29, 7
	s_add_u32 vcc_lo, s98, s92
	s_addc_u32 vcc_hi, s99, 0
	global_load_dwordx4 v[2:5], v249, vcc
	s_nop 0
	s_mul_i32 s29, s27, 0x2400
	s_add_i32 s34, s29, 0xffffdc00
	s_cmp_lg_u32 s27, 0
	s_cselect_b32 s34, s34, 0x9000
	v_add_u32_e32 v92, s34, v195
	ds_read_b128 v[64:67], v92 offset:36864
	ds_read_b128 v[68:71], v92 offset:36896
	ds_read_b128 v[72:75], v92 offset:41472
	ds_read_b128 v[76:79], v92 offset:41504
	ds_read_b128 v[80:83], v92 offset:36928
	ds_read_b128 v[84:87], v92 offset:36960
	ds_read_b128 v[88:91], v92 offset:41536
	ds_read_b128 v[92:95], v92 offset:41568
	s_setprio 3
	v_cvt_pk_bf16_f32 v116, v15, v144
	v_cvt_pk_bf16_f32 v117, v145, v146
	v_cvt_pk_bf16_f32 v118, v147, v148
	v_cvt_pk_bf16_f32 v119, v149, v150
	s_waitcnt lgkmcnt(7)
	s_nop 0
	v_mfma_f32_32x32x16_bf16 v[16:31], v[64:67], v[116:119], v[16:31]
	v_add_f32_e32 v187, v15, v144
	v_add_f32_e32 v187, v187, v145
	v_add_f32_e32 v187, v187, v146
	s_waitcnt lgkmcnt(5)
	v_mfma_f32_32x32x16_bf16 v[32:47], v[72:75], v[116:119], v[32:47]
	v_cvt_pk_bf16_f32 v64, v120, v121
	v_cvt_pk_bf16_f32 v65, v122, v123
	v_cvt_pk_bf16_f32 v66, v151, v184
	v_cvt_pk_bf16_f32 v67, v185, v186
	v_add_f32_e32 v187, v187, v147
	v_add_f32_e32 v187, v187, v148
	v_add_f32_e32 v187, v187, v149
	v_add_f32_e32 v187, v187, v150
	s_nop 0
	v_mfma_f32_32x32x16_bf16 v[16:31], v[68:71], v[64:67], v[16:31]
	v_add_f32_e32 v187, v187, v120
	v_add_f32_e32 v187, v187, v121
	v_add_f32_e32 v187, v187, v122
	v_add_f32_e32 v187, v187, v123
	s_waitcnt lgkmcnt(4)
	v_mfma_f32_32x32x16_bf16 v[32:47], v[76:79], v[64:67], v[32:47]
	v_cvt_pk_bf16_f32 v68, v124, v125
	v_cvt_pk_bf16_f32 v69, v126, v127
	v_cvt_pk_bf16_f32 v70, v128, v129
	v_cvt_pk_bf16_f32 v71, v130, v131
	v_add_f32_e32 v187, v187, v151
	v_add_f32_e32 v187, v187, v184
	v_add_f32_e32 v187, v187, v185
	v_add_f32_e32 v187, v187, v186
	s_waitcnt lgkmcnt(3)
	v_mfma_f32_32x32x16_bf16 v[16:31], v[80:83], v[68:71], v[16:31]
	v_add_f32_e32 v187, v187, v124
	v_add_f32_e32 v187, v187, v125
	v_add_f32_e32 v187, v187, v126
	v_add_f32_e32 v187, v187, v127
	s_waitcnt lgkmcnt(1)
	v_mfma_f32_32x32x16_bf16 v[32:47], v[88:91], v[68:71], v[32:47]
	v_cvt_pk_bf16_f32 v64, v136, v137
	v_cvt_pk_bf16_f32 v65, v138, v139
	v_cvt_pk_bf16_f32 v66, v132, v133
	v_cvt_pk_bf16_f32 v67, v134, v135
	v_add_f32_e32 v187, v187, v128
	v_add_f32_e32 v187, v187, v129
	v_add_f32_e32 v187, v187, v130
	v_add_f32_e32 v187, v187, v131
	s_nop 0
	v_mfma_f32_32x32x16_bf16 v[16:31], v[84:87], v[64:67], v[16:31]
	v_add_f32_e32 v187, v187, v136
	v_add_f32_e32 v187, v187, v137
	v_add_f32_e32 v187, v187, v138
	v_add_f32_e32 v187, v187, v139
	s_waitcnt lgkmcnt(0)
	v_mfma_f32_32x32x16_bf16 v[32:47], v[92:95], v[64:67], v[32:47]
	v_add_f32_e32 v187, v187, v132
	v_add_f32_e32 v187, v187, v133
	v_add_f32_e32 v187, v187, v134
	v_add_f32_e32 v187, v187, v135
	s_setprio 2
	s_waitcnt lgkmcnt(0)
	s_barrier
	ds_read_b128 v[240:243], v195
	ds_read_b128 v[244:247], v195 offset:4608
	ds_read_b128 v[72:75], v195 offset:32
	ds_read_b128 v[76:79], v195 offset:4640
	ds_read_b128 v[80:83], v195 offset:64
	ds_read_b128 v[84:87], v195 offset:4672
	ds_read_b128 v[88:91], v195 offset:96
	ds_read_b128 v[92:95], v195 offset:4704
	v_add_f32_e32 v1, v1, v14
	v_exp_f32_e32 v14, v152
	v_exp_f32_e32 v15, v153
	v_exp_f32_e32 v116, v154
	v_exp_f32_e32 v117, v155
	s_waitcnt lgkmcnt(6)
	v_mfma_f32_32x32x16_bf16 v[136:151], v[240:243], v[180:183], v[48:63]
	v_mfma_f32_32x32x16_bf16 v[120:135], v[244:247], v[180:183], v[48:63]
	v_exp_f32_e32 v118, v156
	v_exp_f32_e32 v119, v157
	v_exp_f32_e32 v184, v158
	v_exp_f32_e32 v185, v159
	s_waitcnt lgkmcnt(5)
	v_mfma_f32_32x32x16_bf16 v[136:151], v[72:75], v[176:179], v[136:151]
	v_exp_f32_e32 v186, v160
	v_exp_f32_e32 v210, v161
	v_exp_f32_e32 v211, v162
	v_exp_f32_e32 v212, v163
	s_waitcnt lgkmcnt(4)
	v_mfma_f32_32x32x16_bf16 v[120:135], v[76:79], v[176:179], v[120:135]
	v_exp_f32_e32 v160, v164
	v_exp_f32_e32 v161, v165
	v_exp_f32_e32 v162, v166
	v_exp_f32_e32 v163, v167
	s_waitcnt lgkmcnt(3)
	v_mfma_f32_32x32x16_bf16 v[136:151], v[80:83], v[172:175], v[136:151]
	v_exp_f32_e32 v164, v96
	v_exp_f32_e32 v165, v97
	v_exp_f32_e32 v166, v98
	v_exp_f32_e32 v167, v99
	s_waitcnt lgkmcnt(2)
	v_mfma_f32_32x32x16_bf16 v[120:135], v[84:87], v[172:175], v[120:135]
	v_exp_f32_e32 v96, v100
	v_exp_f32_e32 v97, v101
	v_exp_f32_e32 v98, v102
	v_exp_f32_e32 v99, v103
	s_waitcnt lgkmcnt(1)
	v_mfma_f32_32x32x16_bf16 v[136:151], v[88:91], v[168:171], v[136:151]
	v_exp_f32_e32 v100, v104
	v_exp_f32_e32 v101, v105
	v_exp_f32_e32 v102, v106
	v_exp_f32_e32 v103, v107
	s_waitcnt lgkmcnt(0)
	v_mfma_f32_32x32x16_bf16 v[120:135], v[92:95], v[168:171], v[120:135]
	v_exp_f32_e32 v104, v108
	v_exp_f32_e32 v105, v109
	v_exp_f32_e32 v106, v110
	v_exp_f32_e32 v107, v111
	s_cmp_gt_i32 s27, 2
	s_cselect_b32 s34, -3, 2
	s_add_i32 s34, s34, s27
	s_mulk_i32 s34, 0x2400
	v_add_u32_e32 v88, s29, v195
	s_min_u32 s29, s13, s12
	s_waitcnt vmcnt(3)
	ds_write_b128 v208, v[10:13] offset:18432
	v_add_u32_e32 v10, s34, v208
	s_lshl_b32 s92, s29, 13
	s_waitcnt vmcnt(2)
	ds_write_b128 v10, v[112:115] offset:36864
	ds_read_b128 v[10:13], v88 offset:41472
	ds_read_b128 v[64:67], v88 offset:36864
	ds_read_b128 v[68:71], v88 offset:36896
	ds_read_b128 v[72:75], v88 offset:41504
	ds_read_b128 v[76:79], v88 offset:36928
	ds_read_b128 v[80:83], v88 offset:41536
	ds_read_b128 v[84:87], v88 offset:36960
	ds_read_b128 v[88:91], v88 offset:41568
	ds_read_b128 v[240:243], v195 offset:9216
	ds_read_b128 v[244:247], v195 offset:13824
	s_add_u32 vcc_lo, s100, s92
	s_addc_u32 vcc_hi, s101, 0
	global_load_dwordx4 v[152:155], v248, vcc
	s_lshl_b32 s92, s28, 7
	s_add_u32 vcc_lo, s98, s92
	s_addc_u32 vcc_hi, s99, 0
	global_load_dwordx4 v[156:159], v249, vcc
	v_add_f32_e32 v1, v1, v187
	s_setprio 1
	v_mov_b32_e32 v109, v136
	v_cvt_pk_bf16_f32 v92, v14, v15
	v_cvt_pk_bf16_f32 v93, v116, v117
	v_cvt_pk_bf16_f32 v94, v118, v119
	v_cvt_pk_bf16_f32 v95, v184, v185
	s_waitcnt lgkmcnt(8)
	s_nop 0
	v_mfma_f32_32x32x16_bf16 v[16:31], v[64:67], v[92:95], v[16:31]
	v_max3_f32 v109, v109, v137, v138
	v_max3_f32 v109, v109, v139, v140
	v_add_f32_e32 v108, v14, v15
	v_add_f32_e32 v108, v108, v116
	v_add_f32_e32 v108, v108, v117
	s_nop 0
	v_mfma_f32_32x32x16_bf16 v[32:47], v[10:13], v[92:95], v[32:47]
	v_cvt_pk_bf16_f32 v64, v186, v210
	v_cvt_pk_bf16_f32 v65, v211, v212
	v_cvt_pk_bf16_f32 v66, v160, v161
	v_cvt_pk_bf16_f32 v67, v162, v163
	v_max3_f32 v109, v109, v141, v142
	v_max3_f32 v109, v109, v143, v144
	v_add_f32_e32 v108, v108, v118
	v_add_f32_e32 v108, v108, v119
	v_add_f32_e32 v108, v108, v184
	v_add_f32_e32 v108, v108, v185
	s_waitcnt lgkmcnt(7)
	v_mfma_f32_32x32x16_bf16 v[16:31], v[68:71], v[64:67], v[16:31]
	v_max3_f32 v109, v109, v145, v146
	v_max3_f32 v109, v109, v147, v148
	v_add_f32_e32 v108, v108, v186
	v_add_f32_e32 v108, v108, v210
	v_add_f32_e32 v108, v108, v211
	v_add_f32_e32 v108, v108, v212
	s_waitcnt lgkmcnt(6)
	v_mfma_f32_32x32x16_bf16 v[32:47], v[72:75], v[64:67], v[32:47]
	v_cvt_pk_bf16_f32 v10, v164, v165
	v_cvt_pk_bf16_f32 v11, v166, v167
	v_cvt_pk_bf16_f32 v12, v96, v97
	v_cvt_pk_bf16_f32 v13, v98, v99
	v_max3_f32 v109, v109, v149, v150
	v_max3_f32 v109, v109, v151, v120
	v_add_f32_e32 v108, v108, v160
	v_add_f32_e32 v108, v108, v161
	v_add_f32_e32 v108, v108, v162
	v_add_f32_e32 v108, v108, v163
	s_waitcnt lgkmcnt(5)
	v_mfma_f32_32x32x16_bf16 v[16:31], v[76:79], v[10:13], v[16:31]
	v_max3_f32 v109, v109, v121, v122
	v_max3_f32 v109, v109, v123, v124
	v_add_f32_e32 v108, v108, v164
	v_add_f32_e32 v108, v108, v165
	v_add_f32_e32 v108, v108, v166
	v_add_f32_e32 v108, v108, v167
	s_waitcnt lgkmcnt(4)
	v_mfma_f32_32x32x16_bf16 v[32:47], v[80:83], v[10:13], v[32:47]
	v_cvt_pk_bf16_f32 v64, v100, v101
	v_cvt_pk_bf16_f32 v65, v102, v103
	v_cvt_pk_bf16_f32 v66, v104, v105
	v_cvt_pk_bf16_f32 v67, v106, v107
	v_max3_f32 v109, v109, v125, v126
	v_max3_f32 v109, v109, v127, v128
	v_add_f32_e32 v108, v108, v96
	v_add_f32_e32 v108, v108, v97
	v_add_f32_e32 v108, v108, v98
	v_add_f32_e32 v108, v108, v99
	s_waitcnt lgkmcnt(3)
	v_mfma_f32_32x32x16_bf16 v[16:31], v[84:87], v[64:67], v[16:31]
	v_max3_f32 v109, v109, v129, v130
	v_max3_f32 v109, v109, v131, v132
	v_add_f32_e32 v108, v108, v100
	v_add_f32_e32 v108, v108, v101
	v_add_f32_e32 v108, v108, v102
	v_add_f32_e32 v108, v108, v103
	s_waitcnt lgkmcnt(2)
	v_mfma_f32_32x32x16_bf16 v[32:47], v[88:91], v[64:67], v[32:47]
	v_max3_f32 v109, v109, v133, v134
	v_max3_f32 v109, v109, v135, v135
	v_add_f32_e32 v108, v108, v104
	v_add_f32_e32 v108, v108, v105
	v_add_f32_e32 v108, v108, v106
	v_add_f32_e32 v108, v108, v107
	s_setprio 0
	ds_read_b128 v[164:167], v195 offset:9248
	ds_read_b128 v[160:163], v195 offset:13856
	ds_read_b128 v[74:77], v195 offset:9280
	ds_read_b128 v[66:69], v195 offset:9312
	ds_read_b128 v[70:73], v195 offset:13888
	ds_read_b128 v[10:13], v195 offset:13920
	v_add_f32_e32 v64, v1, v108
	v_mov_b32_e32 v1, v109
	s_nop 1
	v_permlane32_swap_b32_e32 v109, v1
	v_max_f32_e32 v1, v1, v1
	v_max_f32_e32 v14, v109, v109
	v_max_f32_e32 v1, v14, v1
	v_cmp_lt_f32_e32 vcc, s52, v1
	s_cbranch_vccz .LBB0_663
	v_max_f32_e32 v1, v1, v1
	v_max_f32_e32 v14, 0, v1
	v_add_f32_e32 v209, v209, v14
	v_xor_b32_e32 v48, 0x80000000, v209
	v_pk_add_f32 v[136:137], v[136:137], v[14:15] op_sel_hi:[1,0] neg_lo:[0,1] neg_hi:[0,1]
	v_pk_add_f32 v[120:121], v[120:121], v[14:15] op_sel_hi:[1,0] neg_lo:[0,1] neg_hi:[0,1]
	v_pk_add_f32 v[138:139], v[138:139], v[14:15] op_sel_hi:[1,0] neg_lo:[0,1] neg_hi:[0,1]
	v_pk_add_f32 v[122:123], v[122:123], v[14:15] op_sel_hi:[1,0] neg_lo:[0,1] neg_hi:[0,1]
	v_pk_add_f32 v[140:141], v[140:141], v[14:15] op_sel_hi:[1,0] neg_lo:[0,1] neg_hi:[0,1]
	v_pk_add_f32 v[124:125], v[124:125], v[14:15] op_sel_hi:[1,0] neg_lo:[0,1] neg_hi:[0,1]
	v_pk_add_f32 v[142:143], v[142:143], v[14:15] op_sel_hi:[1,0] neg_lo:[0,1] neg_hi:[0,1]
	v_pk_add_f32 v[126:127], v[126:127], v[14:15] op_sel_hi:[1,0] neg_lo:[0,1] neg_hi:[0,1]
	v_pk_add_f32 v[144:145], v[144:145], v[14:15] op_sel_hi:[1,0] neg_lo:[0,1] neg_hi:[0,1]
	v_pk_add_f32 v[128:129], v[128:129], v[14:15] op_sel_hi:[1,0] neg_lo:[0,1] neg_hi:[0,1]
	v_pk_add_f32 v[146:147], v[146:147], v[14:15] op_sel_hi:[1,0] neg_lo:[0,1] neg_hi:[0,1]
	v_pk_add_f32 v[130:131], v[130:131], v[14:15] op_sel_hi:[1,0] neg_lo:[0,1] neg_hi:[0,1]
	v_pk_add_f32 v[148:149], v[148:149], v[14:15] op_sel_hi:[1,0] neg_lo:[0,1] neg_hi:[0,1]
	v_pk_add_f32 v[132:133], v[132:133], v[14:15] op_sel_hi:[1,0] neg_lo:[0,1] neg_hi:[0,1]
	v_pk_add_f32 v[150:151], v[150:151], v[14:15] op_sel_hi:[1,0] neg_lo:[0,1] neg_hi:[0,1]
	v_pk_add_f32 v[134:135], v[134:135], v[14:15] op_sel_hi:[1,0] neg_lo:[0,1] neg_hi:[0,1]
	v_exp_f32_e64 v14, -v14
	v_mov_b32_e32 v49, v48
	v_mov_b32_e32 v50, v48
	v_mov_b32_e32 v51, v48
	v_mov_b32_e32 v52, v48
	v_mov_b32_e32 v53, v48
	v_mov_b32_e32 v54, v48
	v_mov_b32_e32 v55, v48
	v_mov_b32_e32 v56, v48
	v_mov_b32_e32 v57, v48
	v_mov_b32_e32 v58, v48
	v_mov_b32_e32 v59, v48
	v_mov_b32_e32 v60, v48
	v_mov_b32_e32 v61, v48
	v_mov_b32_e32 v62, v48
	v_mov_b32_e32 v63, v48
	s_nop 11
	v_pk_mul_f32 v[30:31], v[30:31], v[14:15] op_sel_hi:[1,0]
	v_pk_mul_f32 v[28:29], v[28:29], v[14:15] op_sel_hi:[1,0]
	v_pk_mul_f32 v[26:27], v[26:27], v[14:15] op_sel_hi:[1,0]
	v_pk_mul_f32 v[24:25], v[24:25], v[14:15] op_sel_hi:[1,0]
	v_pk_mul_f32 v[22:23], v[22:23], v[14:15] op_sel_hi:[1,0]
	v_pk_mul_f32 v[20:21], v[20:21], v[14:15] op_sel_hi:[1,0]
	v_pk_mul_f32 v[18:19], v[18:19], v[14:15] op_sel_hi:[1,0]
	v_pk_mul_f32 v[16:17], v[16:17], v[14:15] op_sel_hi:[1,0]
	v_pk_mul_f32 v[46:47], v[46:47], v[14:15] op_sel_hi:[1,0]
	v_pk_mul_f32 v[44:45], v[44:45], v[14:15] op_sel_hi:[1,0]
	v_pk_mul_f32 v[42:43], v[42:43], v[14:15] op_sel_hi:[1,0]
	v_pk_mul_f32 v[40:41], v[40:41], v[14:15] op_sel_hi:[1,0]
	v_pk_mul_f32 v[38:39], v[38:39], v[14:15] op_sel_hi:[1,0]
	v_pk_mul_f32 v[36:37], v[36:37], v[14:15] op_sel_hi:[1,0]
	v_pk_mul_f32 v[34:35], v[34:35], v[14:15] op_sel_hi:[1,0]
	v_pk_mul_f32 v[32:33], v[32:33], v[14:15] op_sel_hi:[1,0]
	v_mul_f32_e32 v64, v64, v14
